# v25
# speedup vs baseline: 1.0068x; 1.0068x over previous
.LBB0_269:
	s_add_u32 s26, s24, 0xfff80080
	s_addc_u32 s27, s25, -1
	s_add_i32 s70, 0, 0x10000
	v_add_u32_e32 v148, s70, v154
	ds_read_b128 v[150:153], v148
	ds_read_b128 v[158:161], v148 offset:1024
	ds_read_b128 v[162:165], v148 offset:2048
	ds_read_b128 v[166:169], v148 offset:3072
	s_cmp_eq_u32 s69, 28
	s_cselect_b32 s29, s7, s27
	s_cselect_b32 s28, s6, s26
	s_cselect_b32 s27, s23, s17
	s_cselect_b32 s26, s22, s5
	s_add_i32 m0, s58, 0xc000
	ds_read_b128 v[170:173], v156
	ds_read_b128 v[174:177], v156 offset:1024
	ds_read_b128 v[180:183], v156 offset:2048
	ds_read_b128 v[184:187], v156 offset:3072
	ds_read_b128 v[188:191], v156 offset:4096
	ds_read_b128 v[192:195], v156 offset:5120
	ds_read_b128 v[196:199], v156 offset:6144
	ds_read_b128 v[224:227], v156 offset:7168
	global_load_lds_dwordx4 v146, s[24:25]
	s_add_i32 m0, s58, 0xe000
	s_nop 0
	global_load_lds_dwordx4 v144, s[24:25]
	s_waitcnt lgkmcnt(8)
	s_barrier
	s_waitcnt lgkmcnt(0)
	v_mfma_f32_16x16x32_bf16 v[124:127], v[150:153], v[170:173], v[124:127]
	v_mfma_f32_16x16x32_bf16 v[120:123], v[162:165], v[170:173], v[120:123]
	v_mfma_f32_16x16x32_bf16 v[108:111], v[150:153], v[180:183], v[108:111]
	v_mfma_f32_16x16x32_bf16 v[104:107], v[162:165], v[180:183], v[104:107]
	v_mfma_f32_16x16x32_bf16 v[92:95], v[150:153], v[188:191], v[92:95]
	v_mfma_f32_16x16x32_bf16 v[88:91], v[162:165], v[188:191], v[88:91]
	v_mfma_f32_16x16x32_bf16 v[76:79], v[150:153], v[196:199], v[76:79]
	v_mfma_f32_16x16x32_bf16 v[72:75], v[162:165], v[196:199], v[72:75]
	v_mfma_f32_16x16x32_bf16 v[124:127], v[158:161], v[174:177], v[124:127]
	v_mfma_f32_16x16x32_bf16 v[120:123], v[166:169], v[174:177], v[120:123]
	v_mfma_f32_16x16x32_bf16 v[108:111], v[158:161], v[184:187], v[108:111]
	v_mfma_f32_16x16x32_bf16 v[104:107], v[166:169], v[184:187], v[104:107]
	v_mfma_f32_16x16x32_bf16 v[92:95], v[158:161], v[192:195], v[92:95]
	v_mfma_f32_16x16x32_bf16 v[88:91], v[166:169], v[192:195], v[88:91]
	v_mfma_f32_16x16x32_bf16 v[76:79], v[158:161], v[224:227], v[76:79]
	v_mfma_f32_16x16x32_bf16 v[72:75], v[166:169], v[224:227], v[72:75]
	s_barrier
	s_add_i32 s72, 0, 0x14000
	s_add_i32 s70, s70, s57
	v_add_u32_e32 v148, s72, v154
	s_mov_b32 m0, s70
	ds_read_b128 v[228:231], v148
	ds_read_b128 v[232:235], v148 offset:1024
	ds_read_b128 v[236:239], v148 offset:2048
	ds_read_b128 v[240:243], v148 offset:3072
	global_load_lds_dwordx4 v130, s[26:27]
	s_add_i32 m0, s70, 0x2000
	s_nop 0
	global_load_lds_dwordx4 v134, s[26:27]
	s_barrier
	s_waitcnt lgkmcnt(0)
	v_mfma_f32_16x16x32_bf16 v[116:119], v[228:231], v[170:173], v[116:119]
	v_mfma_f32_16x16x32_bf16 v[112:115], v[236:239], v[170:173], v[112:115]
	v_mfma_f32_16x16x32_bf16 v[100:103], v[228:231], v[180:183], v[100:103]
	v_mfma_f32_16x16x32_bf16 v[96:99], v[236:239], v[180:183], v[96:99]
	v_mfma_f32_16x16x32_bf16 v[84:87], v[228:231], v[188:191], v[84:87]
	v_mfma_f32_16x16x32_bf16 v[80:83], v[236:239], v[188:191], v[80:83]
	v_mfma_f32_16x16x32_bf16 v[68:71], v[228:231], v[196:199], v[68:71]
	v_mfma_f32_16x16x32_bf16 v[64:67], v[236:239], v[196:199], v[64:67]
	v_mfma_f32_16x16x32_bf16 v[116:119], v[232:235], v[174:177], v[116:119]
	v_mfma_f32_16x16x32_bf16 v[112:115], v[240:243], v[174:177], v[112:115]
	v_mfma_f32_16x16x32_bf16 v[100:103], v[232:235], v[184:187], v[100:103]
	v_mfma_f32_16x16x32_bf16 v[96:99], v[240:243], v[184:187], v[96:99]
	v_mfma_f32_16x16x32_bf16 v[84:87], v[232:235], v[192:195], v[84:87]
	v_mfma_f32_16x16x32_bf16 v[80:83], v[240:243], v[192:195], v[80:83]
	v_mfma_f32_16x16x32_bf16 v[68:71], v[232:235], v[224:227], v[68:71]
	v_mfma_f32_16x16x32_bf16 v[64:67], v[240:243], v[224:227], v[64:67]
	s_mov_b32 m0, s58
	s_mov_b64 s[100:101], s[28:29]
	s_barrier
	ds_read_b128 v[170:173], v156 offset:16384
	ds_read_b128 v[174:177], v156 offset:17408
	ds_read_b128 v[180:183], v156 offset:18432
	ds_read_b128 v[184:187], v156 offset:19456
	ds_read_b128 v[188:191], v156 offset:20480
	ds_read_b128 v[192:195], v156 offset:21504
	ds_read_b128 v[196:199], v156 offset:22528
	ds_read_b128 v[224:227], v156 offset:23552
	global_load_lds_dwordx4 v128, s[28:29]
	s_mov_b64 s[100:101], s[28:29]
	s_mov_b32 m0, s59
	s_nop 0
	global_load_lds_dwordx4 v132, s[28:29]
	s_barrier
	s_waitcnt lgkmcnt(0)
	v_mfma_f32_16x16x32_bf16 v[60:63], v[150:153], v[170:173], v[60:63]
	v_mfma_f32_16x16x32_bf16 v[56:59], v[162:165], v[170:173], v[56:59]
	v_mfma_f32_16x16x32_bf16 v[44:47], v[150:153], v[180:183], v[44:47]
	v_mfma_f32_16x16x32_bf16 v[40:43], v[162:165], v[180:183], v[40:43]
	v_mfma_f32_16x16x32_bf16 v[28:31], v[150:153], v[188:191], v[28:31]
	v_mfma_f32_16x16x32_bf16 v[24:27], v[162:165], v[188:191], v[24:27]
	v_mfma_f32_16x16x32_bf16 v[12:15], v[150:153], v[196:199], v[12:15]
	v_mfma_f32_16x16x32_bf16 v[8:11], v[162:165], v[196:199], v[8:11]
	v_mfma_f32_16x16x32_bf16 v[60:63], v[158:161], v[174:177], v[60:63]
	v_mfma_f32_16x16x32_bf16 v[56:59], v[166:169], v[174:177], v[56:59]
	v_mfma_f32_16x16x32_bf16 v[44:47], v[158:161], v[184:187], v[44:47]
	v_mfma_f32_16x16x32_bf16 v[40:43], v[166:169], v[184:187], v[40:43]
	v_mfma_f32_16x16x32_bf16 v[28:31], v[158:161], v[192:195], v[28:31]
	v_mfma_f32_16x16x32_bf16 v[24:27], v[166:169], v[192:195], v[24:27]
	v_mfma_f32_16x16x32_bf16 v[12:15], v[158:161], v[224:227], v[12:15]
	v_mfma_f32_16x16x32_bf16 v[8:11], v[166:169], v[224:227], v[8:11]
	s_barrier
	s_add_u32 s70, s26, 0x80000
	s_addc_u32 s71, s27, 0
	s_add_i32 s72, s72, s57
	s_mov_b32 m0, s72
	s_nop 0
	global_load_lds_dwordx4 v130, s[70:71]
	s_add_i32 m0, s72, 0x2000
	s_nop 0
	global_load_lds_dwordx4 v134, s[70:71]
	s_waitcnt vmcnt(6)
	s_barrier
	v_mfma_f32_16x16x32_bf16 v[52:55], v[228:231], v[170:173], v[52:55]
	v_mfma_f32_16x16x32_bf16 v[48:51], v[236:239], v[170:173], v[48:51]
	v_mfma_f32_16x16x32_bf16 v[36:39], v[228:231], v[180:183], v[36:39]
	v_mfma_f32_16x16x32_bf16 v[32:35], v[236:239], v[180:183], v[32:35]
	v_mfma_f32_16x16x32_bf16 v[20:23], v[228:231], v[188:191], v[20:23]
	v_mfma_f32_16x16x32_bf16 v[16:19], v[236:239], v[188:191], v[16:19]
	v_mfma_f32_16x16x32_bf16 v[4:7], v[228:231], v[196:199], v[4:7]
	v_mfma_f32_16x16x32_bf16 v[0:3], v[236:239], v[196:199], v[0:3]
	v_mfma_f32_16x16x32_bf16 v[52:55], v[232:235], v[174:177], v[52:55]
	v_mfma_f32_16x16x32_bf16 v[48:51], v[240:243], v[174:177], v[48:51]
	v_mfma_f32_16x16x32_bf16 v[36:39], v[232:235], v[184:187], v[36:39]
	v_mfma_f32_16x16x32_bf16 v[32:35], v[240:243], v[184:187], v[32:35]
	v_mfma_f32_16x16x32_bf16 v[20:23], v[232:235], v[192:195], v[20:23]
	v_mfma_f32_16x16x32_bf16 v[16:19], v[240:243], v[192:195], v[16:19]
	v_mfma_f32_16x16x32_bf16 v[4:7], v[232:235], v[224:227], v[4:7]
	v_mfma_f32_16x16x32_bf16 v[0:3], v[240:243], v[224:227], v[0:3]
	s_add_i32 s70, 0, 0x18000
	v_add_u32_e32 v148, s70, v154
	s_barrier
	ds_read_b128 v[150:153], v148
	ds_read_b128 v[158:161], v148 offset:1024
	ds_read_b128 v[162:165], v148 offset:2048
	ds_read_b128 v[166:169], v148 offset:3072
	s_add_u32 s28, s28, 0x80000
	s_addc_u32 s29, s29, 0
	s_mov_b32 m0, s60
	ds_read_b128 v[170:173], v156 offset:32768
	ds_read_b128 v[174:177], v156 offset:33792
	ds_read_b128 v[180:183], v156 offset:34816
	ds_read_b128 v[184:187], v156 offset:35840
	ds_read_b128 v[188:191], v156 offset:36864
	ds_read_b128 v[192:195], v156 offset:37888
	ds_read_b128 v[196:199], v156 offset:38912
	ds_read_b128 v[224:227], v156 offset:39936
	global_load_lds_dwordx4 v128, s[28:29]
	s_mov_b32 m0, s61
	s_nop 0
	global_load_lds_dwordx4 v132, s[28:29]
	s_waitcnt lgkmcnt(8)
	s_barrier
	s_waitcnt lgkmcnt(0)
	v_mfma_f32_16x16x32_bf16 v[124:127], v[150:153], v[170:173], v[124:127]
	v_mfma_f32_16x16x32_bf16 v[120:123], v[162:165], v[170:173], v[120:123]
	v_mfma_f32_16x16x32_bf16 v[108:111], v[150:153], v[180:183], v[108:111]
	v_mfma_f32_16x16x32_bf16 v[104:107], v[162:165], v[180:183], v[104:107]
	v_mfma_f32_16x16x32_bf16 v[92:95], v[150:153], v[188:191], v[92:95]
	v_mfma_f32_16x16x32_bf16 v[88:91], v[162:165], v[188:191], v[88:91]
	v_mfma_f32_16x16x32_bf16 v[76:79], v[150:153], v[196:199], v[76:79]
	v_mfma_f32_16x16x32_bf16 v[72:75], v[162:165], v[196:199], v[72:75]
	v_mfma_f32_16x16x32_bf16 v[124:127], v[158:161], v[174:177], v[124:127]
	v_mfma_f32_16x16x32_bf16 v[120:123], v[166:169], v[174:177], v[120:123]
	v_mfma_f32_16x16x32_bf16 v[108:111], v[158:161], v[184:187], v[108:111]
	v_mfma_f32_16x16x32_bf16 v[104:107], v[166:169], v[184:187], v[104:107]
	v_mfma_f32_16x16x32_bf16 v[92:95], v[158:161], v[192:195], v[92:95]
	v_mfma_f32_16x16x32_bf16 v[88:91], v[166:169], v[192:195], v[88:91]
	v_mfma_f32_16x16x32_bf16 v[76:79], v[158:161], v[224:227], v[76:79]
	v_mfma_f32_16x16x32_bf16 v[72:75], v[166:169], v[224:227], v[72:75]
	s_barrier
	s_add_i32 s28, 0, 0x1c000
	s_add_i32 s29, s70, s57
	v_add_u32_e32 v148, s28, v154
	s_add_i32 m0, s29, 0xffffff80
	ds_read_b128 v[228:231], v148
	ds_read_b128 v[232:235], v148 offset:1024
	ds_read_b128 v[236:239], v148 offset:2048
	ds_read_b128 v[240:243], v148 offset:3072
	global_load_lds_dwordx4 v130, s[26:27] offset:128
	s_add_i32 m0, s29, 0x1f80
	s_nop 0
	global_load_lds_dwordx4 v134, s[26:27] offset:128
	s_barrier
	s_waitcnt lgkmcnt(0)
	v_mfma_f32_16x16x32_bf16 v[116:119], v[228:231], v[170:173], v[116:119]
	v_mfma_f32_16x16x32_bf16 v[112:115], v[236:239], v[170:173], v[112:115]
	v_mfma_f32_16x16x32_bf16 v[100:103], v[228:231], v[180:183], v[100:103]
	v_mfma_f32_16x16x32_bf16 v[96:99], v[236:239], v[180:183], v[96:99]
	v_mfma_f32_16x16x32_bf16 v[84:87], v[228:231], v[188:191], v[84:87]
	v_mfma_f32_16x16x32_bf16 v[80:83], v[236:239], v[188:191], v[80:83]
	v_mfma_f32_16x16x32_bf16 v[68:71], v[228:231], v[196:199], v[68:71]
	v_mfma_f32_16x16x32_bf16 v[64:67], v[236:239], v[196:199], v[64:67]
	v_mfma_f32_16x16x32_bf16 v[116:119], v[232:235], v[174:177], v[116:119]
	v_mfma_f32_16x16x32_bf16 v[112:115], v[240:243], v[174:177], v[112:115]
	v_mfma_f32_16x16x32_bf16 v[100:103], v[232:235], v[184:187], v[100:103]
	v_mfma_f32_16x16x32_bf16 v[96:99], v[240:243], v[184:187], v[96:99]
	v_mfma_f32_16x16x32_bf16 v[84:87], v[232:235], v[192:195], v[84:87]
	v_mfma_f32_16x16x32_bf16 v[80:83], v[240:243], v[192:195], v[80:83]
	v_mfma_f32_16x16x32_bf16 v[68:71], v[232:235], v[224:227], v[68:71]
	v_mfma_f32_16x16x32_bf16 v[64:67], v[240:243], v[224:227], v[64:67]
	s_add_i32 m0, s62, 0xffffff80
	s_barrier
	ds_read_b128 v[170:173], v156 offset:49152
	ds_read_b128 v[174:177], v156 offset:50176
	ds_read_b128 v[180:183], v156 offset:51200
	ds_read_b128 v[184:187], v156 offset:52224
	ds_read_b128 v[188:191], v156 offset:53248
	ds_read_b128 v[192:195], v156 offset:54272
	ds_read_b128 v[196:199], v156 offset:55296
	ds_read_b128 v[224:227], v156 offset:56320
	global_load_lds_dwordx4 v128, s[100:101] offset:128
	s_add_i32 m0, s63, 0xffffff80
	s_nop 0
	global_load_lds_dwordx4 v132, s[100:101] offset:128
	s_barrier
	s_waitcnt lgkmcnt(0)
	v_mfma_f32_16x16x32_bf16 v[60:63], v[150:153], v[170:173], v[60:63]
	v_mfma_f32_16x16x32_bf16 v[56:59], v[162:165], v[170:173], v[56:59]
	v_mfma_f32_16x16x32_bf16 v[44:47], v[150:153], v[180:183], v[44:47]
	v_mfma_f32_16x16x32_bf16 v[40:43], v[162:165], v[180:183], v[40:43]
	v_mfma_f32_16x16x32_bf16 v[28:31], v[150:153], v[188:191], v[28:31]
	v_mfma_f32_16x16x32_bf16 v[24:27], v[162:165], v[188:191], v[24:27]
	v_mfma_f32_16x16x32_bf16 v[12:15], v[150:153], v[196:199], v[12:15]
	v_mfma_f32_16x16x32_bf16 v[8:11], v[162:165], v[196:199], v[8:11]
	v_mfma_f32_16x16x32_bf16 v[60:63], v[158:161], v[174:177], v[60:63]
	v_mfma_f32_16x16x32_bf16 v[56:59], v[166:169], v[174:177], v[56:59]
	v_mfma_f32_16x16x32_bf16 v[44:47], v[158:161], v[184:187], v[44:47]
	v_mfma_f32_16x16x32_bf16 v[40:43], v[166:169], v[184:187], v[40:43]
	v_mfma_f32_16x16x32_bf16 v[28:31], v[158:161], v[192:195], v[28:31]
	v_mfma_f32_16x16x32_bf16 v[24:27], v[166:169], v[192:195], v[24:27]
	v_mfma_f32_16x16x32_bf16 v[12:15], v[158:161], v[224:227], v[12:15]
	v_mfma_f32_16x16x32_bf16 v[8:11], v[166:169], v[224:227], v[8:11]
	s_barrier
	s_add_u32 s26, s26, 0x80080
	s_addc_u32 s27, s27, 0
	s_add_i32 s28, s28, s57
	s_mov_b32 m0, s28
	s_nop 0
	global_load_lds_dwordx4 v130, s[26:27]
	s_add_i32 m0, s28, 0x2000
	s_nop 0
	global_load_lds_dwordx4 v134, s[26:27]
	s_waitcnt vmcnt(6)
	s_barrier
	v_mfma_f32_16x16x32_bf16 v[52:55], v[228:231], v[170:173], v[52:55]
	v_mfma_f32_16x16x32_bf16 v[48:51], v[236:239], v[170:173], v[48:51]
	v_mfma_f32_16x16x32_bf16 v[36:39], v[228:231], v[180:183], v[36:39]
	v_mfma_f32_16x16x32_bf16 v[32:35], v[236:239], v[180:183], v[32:35]
	v_mfma_f32_16x16x32_bf16 v[20:23], v[228:231], v[188:191], v[20:23]
	v_mfma_f32_16x16x32_bf16 v[16:19], v[236:239], v[188:191], v[16:19]
	v_mfma_f32_16x16x32_bf16 v[4:7], v[228:231], v[196:199], v[4:7]
	v_mfma_f32_16x16x32_bf16 v[0:3], v[236:239], v[196:199], v[0:3]
	v_mfma_f32_16x16x32_bf16 v[52:55], v[232:235], v[174:177], v[52:55]
	v_mfma_f32_16x16x32_bf16 v[48:51], v[240:243], v[174:177], v[48:51]
	v_mfma_f32_16x16x32_bf16 v[36:39], v[232:235], v[184:187], v[36:39]
	v_mfma_f32_16x16x32_bf16 v[32:35], v[240:243], v[184:187], v[32:35]
	v_mfma_f32_16x16x32_bf16 v[20:23], v[232:235], v[192:195], v[20:23]
	v_mfma_f32_16x16x32_bf16 v[16:19], v[240:243], v[192:195], v[16:19]
	v_mfma_f32_16x16x32_bf16 v[4:7], v[232:235], v[224:227], v[4:7]
	v_mfma_f32_16x16x32_bf16 v[0:3], v[240:243], v[224:227], v[0:3]
	s_add_i32 s69, s69, 2
	s_add_u32 s5, s5, 0x100
	s_addc_u32 s17, s17, 0
	s_add_u32 s24, s24, 0x100
	s_addc_u32 s25, s25, 0
	s_cmp_gt_u32 s69, 29
	s_barrier
	s_cbranch_scc0 .LBB0_269
	s_lshl_b32 s5, s68, 8
	v_lshl_add_u32 v158, s4, 8, v137
	v_or_b32_e32 v148, s5, v136
	s_addk_i32 s5, 0xf000
	s_lshr_b32 s4, s5, 2
	v_and_b32_e32 v159, 0xffffff80, v158
	s_and_b32 s22, s4, 0x3ffffe00
	v_add_u32_e32 v160, v159, v155
	v_add_u32_e32 v150, s22, v160
	s_lshl_b32 s17, s68, 9
	v_ashrrev_i32_e32 v151, 31, v150
	v_lshlrev_b64 v[152:153], 13, v[150:151]
	v_add_u32_e32 v150, s17, v160
	v_ashrrev_i32_e32 v151, 31, v150
	v_cmp_ne_u32_e64 s[6:7], 0, v149
	s_movk_i32 s4, 0xfff
	v_lshlrev_b64 v[150:151], 10, v[150:151]
	s_and_b64 vcc, exec, s[6:7]
	v_cmp_lt_i32_e64 s[4:5], s4, v148
	v_cvt_pk_bf16_f32 v124, v124, v125
	v_cvt_pk_bf16_f32 v125, v126, v127
	v_cvt_pk_bf16_f32 v126, v120, v121
	v_cvt_pk_bf16_f32 v127, v122, v123
	s_cbranch_vccz .LBB0_290
	s_and_saveexec_b64 s[24:25], s[4:5]
	s_xor_b64 s[4:5], exec, s[24:25]
	v_and_b32_e32 v122, 0x778, v148
	v_lshl_add_u64 v[120:121], v[138:139], 0, v[152:153]
	v_lshlrev_b32_e32 v178, 1, v122
	v_lshl_add_u64 v[122:123], v[120:121], 0, v[178:179]
	s_andn2_saveexec_b64 s[4:5], s[4:5]
	v_lshl_add_u64 v[122:123], v[142:143], 0, v[150:151]
	s_or_b64 exec, exec, s[4:5]
	s_movk_i32 s4, 0x1a00
	v_mad_i64_i32 v[120:121], s[4:5], v158, s4, 0
	s_cbranch_execnz .LBB0_277

.LBB0_935:
	s_add_u32 s12, s10, 0xf4c00080
	s_addc_u32 s13, s11, -1
	s_cmp_lg_u32 s28, 60
	s_cselect_b32 s12, s12, 0
	s_cselect_b32 s13, s13, 0
	s_add_u32 s14, s6, s12
	s_addc_u32 s15, s7, s13
	s_add_i32 s29, 0, 0x10000
	v_add_u32_e32 v150, s29, v140
	ds_read_b128 v[142:145], v150
	ds_read_b128 v[146:149], v150 offset:1024
	ds_read_b128 v[154:157], v150 offset:2048
	ds_read_b128 v[158:161], v150 offset:3072
	s_add_u32 s12, s8, s12
	s_addc_u32 s13, s9, s13
	v_lshl_add_u64 v[150:151], v[136:137], 0, s[10:11]
	s_add_i32 m0, s22, 0xc000
	ds_read_b128 v[162:165], v141
	ds_read_b128 v[166:169], v141 offset:1024
	ds_read_b128 v[170:173], v141 offset:2048
	ds_read_b128 v[174:177], v141 offset:3072
	ds_read_b128 v[180:183], v141 offset:4096
	ds_read_b128 v[184:187], v141 offset:5120
	ds_read_b128 v[188:191], v141 offset:6144
	ds_read_b128 v[192:195], v141 offset:7168
	global_load_lds_dwordx4 v[150:151], off
	v_lshl_add_u64 v[150:151], v[134:135], 0, s[10:11]
	s_add_i32 m0, s22, 0xe000
	s_nop 0
	global_load_lds_dwordx4 v[150:151], off
	s_waitcnt lgkmcnt(8)
	s_barrier
	s_waitcnt lgkmcnt(0)
	v_mfma_f32_16x16x32_bf16 v[124:127], v[142:145], v[162:165], v[124:127]
	v_mfma_f32_16x16x32_bf16 v[120:123], v[154:157], v[162:165], v[120:123]
	v_mfma_f32_16x16x32_bf16 v[116:119], v[142:145], v[170:173], v[116:119]
	v_mfma_f32_16x16x32_bf16 v[108:111], v[154:157], v[170:173], v[108:111]
	v_mfma_f32_16x16x32_bf16 v[100:103], v[142:145], v[180:183], v[100:103]
	v_mfma_f32_16x16x32_bf16 v[92:95], v[154:157], v[180:183], v[92:95]
	v_mfma_f32_16x16x32_bf16 v[84:87], v[142:145], v[188:191], v[84:87]
	v_mfma_f32_16x16x32_bf16 v[76:79], v[154:157], v[188:191], v[76:79]
	v_mfma_f32_16x16x32_bf16 v[124:127], v[146:149], v[166:169], v[124:127]
	v_mfma_f32_16x16x32_bf16 v[120:123], v[158:161], v[166:169], v[120:123]
	v_mfma_f32_16x16x32_bf16 v[116:119], v[146:149], v[174:177], v[116:119]
	v_mfma_f32_16x16x32_bf16 v[108:111], v[158:161], v[174:177], v[108:111]
	v_mfma_f32_16x16x32_bf16 v[100:103], v[146:149], v[184:187], v[100:103]
	v_mfma_f32_16x16x32_bf16 v[92:95], v[158:161], v[184:187], v[92:95]
	v_mfma_f32_16x16x32_bf16 v[84:87], v[146:149], v[192:195], v[84:87]
	v_mfma_f32_16x16x32_bf16 v[76:79], v[158:161], v[192:195], v[76:79]
	s_barrier
	s_add_i32 s35, 0, 0x14000
	v_add_u32_e32 v150, s35, v140
	s_add_i32 s29, s29, s16
	ds_read_b128 v[196:199], v150
	ds_read_b128 v[224:227], v150 offset:1024
	ds_read_b128 v[228:231], v150 offset:2048
	ds_read_b128 v[232:235], v150 offset:3072
	s_mov_b32 m0, s29
	global_load_lds_dwordx4 v178, s[12:13]
	s_add_i32 m0, s29, 0x2000
	s_nop 0
	global_load_lds_dwordx4 v128, s[12:13]
	s_barrier
	s_waitcnt lgkmcnt(0)
	v_mfma_f32_16x16x32_bf16 v[112:115], v[196:199], v[162:165], v[112:115]
	v_mfma_f32_16x16x32_bf16 v[104:107], v[228:231], v[162:165], v[104:107]
	v_mfma_f32_16x16x32_bf16 v[96:99], v[196:199], v[170:173], v[96:99]
	v_mfma_f32_16x16x32_bf16 v[88:91], v[228:231], v[170:173], v[88:91]
	v_mfma_f32_16x16x32_bf16 v[80:83], v[196:199], v[180:183], v[80:83]
	v_mfma_f32_16x16x32_bf16 v[72:75], v[228:231], v[180:183], v[72:75]
	v_mfma_f32_16x16x32_bf16 v[68:71], v[196:199], v[188:191], v[68:71]
	v_mfma_f32_16x16x32_bf16 v[64:67], v[228:231], v[188:191], v[64:67]
	v_mfma_f32_16x16x32_bf16 v[112:115], v[224:227], v[166:169], v[112:115]
	v_mfma_f32_16x16x32_bf16 v[104:107], v[232:235], v[166:169], v[104:107]
	v_mfma_f32_16x16x32_bf16 v[96:99], v[224:227], v[174:177], v[96:99]
	v_mfma_f32_16x16x32_bf16 v[88:91], v[232:235], v[174:177], v[88:91]
	v_mfma_f32_16x16x32_bf16 v[80:83], v[224:227], v[184:187], v[80:83]
	v_mfma_f32_16x16x32_bf16 v[72:75], v[232:235], v[184:187], v[72:75]
	v_mfma_f32_16x16x32_bf16 v[68:71], v[224:227], v[192:195], v[68:71]
	v_mfma_f32_16x16x32_bf16 v[64:67], v[232:235], v[192:195], v[64:67]
	s_mov_b32 m0, s22
	s_mov_b64 s[100:101], s[14:15]
	s_barrier
	ds_read_b128 v[162:165], v141 offset:16384
	ds_read_b128 v[166:169], v141 offset:17408
	ds_read_b128 v[170:173], v141 offset:18432
	ds_read_b128 v[174:177], v141 offset:19456
	ds_read_b128 v[180:183], v141 offset:20480
	ds_read_b128 v[184:187], v141 offset:21504
	ds_read_b128 v[188:191], v141 offset:22528
	ds_read_b128 v[192:195], v141 offset:23552
	global_load_lds_dwordx4 v132, s[14:15]
	s_mov_b64 s[100:101], s[14:15]
	s_mov_b32 m0, s23
	s_nop 0
	global_load_lds_dwordx4 v130, s[14:15]
	s_barrier
	s_waitcnt lgkmcnt(0)
	v_mfma_f32_16x16x32_bf16 v[60:63], v[142:145], v[162:165], v[60:63]
	v_mfma_f32_16x16x32_bf16 v[56:59], v[154:157], v[162:165], v[56:59]
	v_mfma_f32_16x16x32_bf16 v[52:55], v[142:145], v[170:173], v[52:55]
	v_mfma_f32_16x16x32_bf16 v[44:47], v[154:157], v[170:173], v[44:47]
	v_mfma_f32_16x16x32_bf16 v[36:39], v[142:145], v[180:183], v[36:39]
	v_mfma_f32_16x16x32_bf16 v[28:31], v[154:157], v[180:183], v[28:31]
	v_mfma_f32_16x16x32_bf16 v[20:23], v[142:145], v[188:191], v[20:23]
	v_mfma_f32_16x16x32_bf16 v[12:15], v[154:157], v[188:191], v[12:15]
	v_mfma_f32_16x16x32_bf16 v[60:63], v[146:149], v[166:169], v[60:63]
	v_mfma_f32_16x16x32_bf16 v[56:59], v[158:161], v[166:169], v[56:59]
	v_mfma_f32_16x16x32_bf16 v[52:55], v[146:149], v[174:177], v[52:55]
	v_mfma_f32_16x16x32_bf16 v[44:47], v[158:161], v[174:177], v[44:47]
	v_mfma_f32_16x16x32_bf16 v[36:39], v[146:149], v[184:187], v[36:39]
	v_mfma_f32_16x16x32_bf16 v[28:31], v[158:161], v[184:187], v[28:31]
	v_mfma_f32_16x16x32_bf16 v[20:23], v[146:149], v[192:195], v[20:23]
	v_mfma_f32_16x16x32_bf16 v[12:15], v[158:161], v[192:195], v[12:15]
	s_barrier
	s_add_u32 s30, s12, 0x100000
	s_addc_u32 s31, s13, 0
	s_add_i32 s29, s35, s16
	s_mov_b32 m0, s29
	s_nop 0
	global_load_lds_dwordx4 v178, s[30:31]
	s_add_i32 m0, s29, 0x2000
	s_nop 0
	global_load_lds_dwordx4 v128, s[30:31]
	s_waitcnt vmcnt(6)
	s_barrier
	v_mfma_f32_16x16x32_bf16 v[48:51], v[196:199], v[162:165], v[48:51]
	v_mfma_f32_16x16x32_bf16 v[40:43], v[228:231], v[162:165], v[40:43]
	v_mfma_f32_16x16x32_bf16 v[32:35], v[196:199], v[170:173], v[32:35]
	v_mfma_f32_16x16x32_bf16 v[24:27], v[228:231], v[170:173], v[24:27]
	v_mfma_f32_16x16x32_bf16 v[16:19], v[196:199], v[180:183], v[16:19]
	v_mfma_f32_16x16x32_bf16 v[8:11], v[228:231], v[180:183], v[8:11]
	v_mfma_f32_16x16x32_bf16 v[4:7], v[196:199], v[188:191], v[4:7]
	v_mfma_f32_16x16x32_bf16 v[0:3], v[228:231], v[188:191], v[0:3]
	v_mfma_f32_16x16x32_bf16 v[48:51], v[224:227], v[166:169], v[48:51]
	v_mfma_f32_16x16x32_bf16 v[40:43], v[232:235], v[166:169], v[40:43]
	v_mfma_f32_16x16x32_bf16 v[32:35], v[224:227], v[174:177], v[32:35]
	v_mfma_f32_16x16x32_bf16 v[24:27], v[232:235], v[174:177], v[24:27]
	v_mfma_f32_16x16x32_bf16 v[16:19], v[224:227], v[184:187], v[16:19]
	v_mfma_f32_16x16x32_bf16 v[8:11], v[232:235], v[184:187], v[8:11]
	v_mfma_f32_16x16x32_bf16 v[4:7], v[224:227], v[192:195], v[4:7]
	v_mfma_f32_16x16x32_bf16 v[0:3], v[232:235], v[192:195], v[0:3]
	s_add_i32 s29, 0, 0x18000
	v_add_u32_e32 v153, s29, v140
	s_barrier
	ds_read_b128 v[142:145], v153
	ds_read_b128 v[146:149], v153 offset:1024
	ds_read_b128 v[154:157], v153 offset:2048
	ds_read_b128 v[158:161], v153 offset:3072
	s_add_u32 s14, s14, 0x100000
	s_addc_u32 s15, s15, 0
	s_mov_b32 m0, s24
	ds_read_b128 v[162:165], v141 offset:32768
	ds_read_b128 v[166:169], v141 offset:33792
	ds_read_b128 v[170:173], v141 offset:34816
	ds_read_b128 v[174:177], v141 offset:35840
	ds_read_b128 v[180:183], v141 offset:36864
	ds_read_b128 v[184:187], v141 offset:37888
	ds_read_b128 v[188:191], v141 offset:38912
	ds_read_b128 v[192:195], v141 offset:39936
	global_load_lds_dwordx4 v132, s[14:15]
	s_mov_b32 m0, s25
	s_nop 0
	global_load_lds_dwordx4 v130, s[14:15]
	s_waitcnt lgkmcnt(8)
	s_barrier
	s_waitcnt lgkmcnt(0)
	v_mfma_f32_16x16x32_bf16 v[124:127], v[142:145], v[162:165], v[124:127]
	v_mfma_f32_16x16x32_bf16 v[120:123], v[154:157], v[162:165], v[120:123]
	v_mfma_f32_16x16x32_bf16 v[116:119], v[142:145], v[170:173], v[116:119]
	v_mfma_f32_16x16x32_bf16 v[108:111], v[154:157], v[170:173], v[108:111]
	v_mfma_f32_16x16x32_bf16 v[100:103], v[142:145], v[180:183], v[100:103]
	v_mfma_f32_16x16x32_bf16 v[92:95], v[154:157], v[180:183], v[92:95]
	v_mfma_f32_16x16x32_bf16 v[84:87], v[142:145], v[188:191], v[84:87]
	v_mfma_f32_16x16x32_bf16 v[76:79], v[154:157], v[188:191], v[76:79]
	v_mfma_f32_16x16x32_bf16 v[124:127], v[146:149], v[166:169], v[124:127]
	v_mfma_f32_16x16x32_bf16 v[120:123], v[158:161], v[166:169], v[120:123]
	v_mfma_f32_16x16x32_bf16 v[116:119], v[146:149], v[174:177], v[116:119]
	v_mfma_f32_16x16x32_bf16 v[108:111], v[158:161], v[174:177], v[108:111]
	v_mfma_f32_16x16x32_bf16 v[100:103], v[146:149], v[184:187], v[100:103]
	v_mfma_f32_16x16x32_bf16 v[92:95], v[158:161], v[184:187], v[92:95]
	v_mfma_f32_16x16x32_bf16 v[84:87], v[146:149], v[192:195], v[84:87]
	v_mfma_f32_16x16x32_bf16 v[76:79], v[158:161], v[192:195], v[76:79]
	s_barrier
	s_add_i32 s14, 0, 0x1c000
	s_add_i32 s15, s29, s16
	v_add_u32_e32 v153, s14, v140
	s_add_i32 m0, s15, 0xffffff80
	ds_read_b128 v[196:199], v153
	ds_read_b128 v[224:227], v153 offset:1024
	ds_read_b128 v[228:231], v153 offset:2048
	ds_read_b128 v[232:235], v153 offset:3072
	global_load_lds_dwordx4 v178, s[12:13] offset:128
	s_add_i32 m0, s15, 0x1f80
	s_nop 0
	global_load_lds_dwordx4 v128, s[12:13] offset:128
	s_barrier
	s_waitcnt lgkmcnt(0)
	v_mfma_f32_16x16x32_bf16 v[112:115], v[196:199], v[162:165], v[112:115]
	v_mfma_f32_16x16x32_bf16 v[104:107], v[228:231], v[162:165], v[104:107]
	v_mfma_f32_16x16x32_bf16 v[96:99], v[196:199], v[170:173], v[96:99]
	v_mfma_f32_16x16x32_bf16 v[88:91], v[228:231], v[170:173], v[88:91]
	v_mfma_f32_16x16x32_bf16 v[80:83], v[196:199], v[180:183], v[80:83]
	v_mfma_f32_16x16x32_bf16 v[72:75], v[228:231], v[180:183], v[72:75]
	v_mfma_f32_16x16x32_bf16 v[68:71], v[196:199], v[188:191], v[68:71]
	v_mfma_f32_16x16x32_bf16 v[64:67], v[228:231], v[188:191], v[64:67]
	v_mfma_f32_16x16x32_bf16 v[112:115], v[224:227], v[166:169], v[112:115]
	v_mfma_f32_16x16x32_bf16 v[104:107], v[232:235], v[166:169], v[104:107]
	v_mfma_f32_16x16x32_bf16 v[96:99], v[224:227], v[174:177], v[96:99]
	v_mfma_f32_16x16x32_bf16 v[88:91], v[232:235], v[174:177], v[88:91]
	v_mfma_f32_16x16x32_bf16 v[80:83], v[224:227], v[184:187], v[80:83]
	v_mfma_f32_16x16x32_bf16 v[72:75], v[232:235], v[184:187], v[72:75]
	v_mfma_f32_16x16x32_bf16 v[68:71], v[224:227], v[192:195], v[68:71]
	v_mfma_f32_16x16x32_bf16 v[64:67], v[232:235], v[192:195], v[64:67]
	s_add_i32 m0, s26, 0xffffff80
	s_barrier
	ds_read_b128 v[162:165], v141 offset:49152
	ds_read_b128 v[166:169], v141 offset:50176
	ds_read_b128 v[170:173], v141 offset:51200
	ds_read_b128 v[174:177], v141 offset:52224
	ds_read_b128 v[180:183], v141 offset:53248
	ds_read_b128 v[184:187], v141 offset:54272
	ds_read_b128 v[188:191], v141 offset:55296
	ds_read_b128 v[192:195], v141 offset:56320
	global_load_lds_dwordx4 v132, s[100:101] offset:128
	s_add_i32 m0, s27, 0xffffff80
	s_nop 0
	global_load_lds_dwordx4 v130, s[100:101] offset:128
	s_barrier
	s_waitcnt lgkmcnt(0)
	v_mfma_f32_16x16x32_bf16 v[60:63], v[142:145], v[162:165], v[60:63]
	v_mfma_f32_16x16x32_bf16 v[56:59], v[154:157], v[162:165], v[56:59]
	v_mfma_f32_16x16x32_bf16 v[52:55], v[142:145], v[170:173], v[52:55]
	v_mfma_f32_16x16x32_bf16 v[44:47], v[154:157], v[170:173], v[44:47]
	v_mfma_f32_16x16x32_bf16 v[36:39], v[142:145], v[180:183], v[36:39]
	v_mfma_f32_16x16x32_bf16 v[28:31], v[154:157], v[180:183], v[28:31]
	v_mfma_f32_16x16x32_bf16 v[20:23], v[142:145], v[188:191], v[20:23]
	v_mfma_f32_16x16x32_bf16 v[12:15], v[154:157], v[188:191], v[12:15]
	v_mfma_f32_16x16x32_bf16 v[60:63], v[146:149], v[166:169], v[60:63]
	v_mfma_f32_16x16x32_bf16 v[56:59], v[158:161], v[166:169], v[56:59]
	v_mfma_f32_16x16x32_bf16 v[52:55], v[146:149], v[174:177], v[52:55]
	v_mfma_f32_16x16x32_bf16 v[44:47], v[158:161], v[174:177], v[44:47]
	v_mfma_f32_16x16x32_bf16 v[36:39], v[146:149], v[184:187], v[36:39]
	v_mfma_f32_16x16x32_bf16 v[28:31], v[158:161], v[184:187], v[28:31]
	v_mfma_f32_16x16x32_bf16 v[20:23], v[146:149], v[192:195], v[20:23]
	v_mfma_f32_16x16x32_bf16 v[12:15], v[158:161], v[192:195], v[12:15]
	s_barrier
	s_add_u32 s12, s12, 0x100080
	s_addc_u32 s13, s13, 0
	s_add_i32 s14, s14, s16
	s_mov_b32 m0, s14
	s_nop 0
	global_load_lds_dwordx4 v178, s[12:13]
	s_add_i32 m0, s14, 0x2000
	s_nop 0
	global_load_lds_dwordx4 v128, s[12:13]
	s_waitcnt vmcnt(6)
	s_barrier
	v_mfma_f32_16x16x32_bf16 v[48:51], v[196:199], v[162:165], v[48:51]
	v_mfma_f32_16x16x32_bf16 v[40:43], v[228:231], v[162:165], v[40:43]
	v_mfma_f32_16x16x32_bf16 v[32:35], v[196:199], v[170:173], v[32:35]
	v_mfma_f32_16x16x32_bf16 v[24:27], v[228:231], v[170:173], v[24:27]
	v_mfma_f32_16x16x32_bf16 v[16:19], v[196:199], v[180:183], v[16:19]
	v_mfma_f32_16x16x32_bf16 v[8:11], v[228:231], v[180:183], v[8:11]
	v_mfma_f32_16x16x32_bf16 v[4:7], v[196:199], v[188:191], v[4:7]
	v_mfma_f32_16x16x32_bf16 v[0:3], v[228:231], v[188:191], v[0:3]
	v_mfma_f32_16x16x32_bf16 v[48:51], v[224:227], v[166:169], v[48:51]
	v_mfma_f32_16x16x32_bf16 v[40:43], v[232:235], v[166:169], v[40:43]
	v_mfma_f32_16x16x32_bf16 v[32:35], v[224:227], v[174:177], v[32:35]
	v_mfma_f32_16x16x32_bf16 v[24:27], v[232:235], v[174:177], v[24:27]
	v_mfma_f32_16x16x32_bf16 v[16:19], v[224:227], v[184:187], v[16:19]
	v_mfma_f32_16x16x32_bf16 v[8:11], v[232:235], v[184:187], v[8:11]
	v_mfma_f32_16x16x32_bf16 v[4:7], v[224:227], v[192:195], v[4:7]
	v_mfma_f32_16x16x32_bf16 v[0:3], v[232:235], v[192:195], v[0:3]
	s_add_i32 s28, s28, 2
	s_add_u32 s10, s10, 0x100
	s_addc_u32 s11, s11, 0
	s_cmp_gt_u32 s28, 61
	s_barrier
	s_cbranch_scc0 .LBB0_935
	v_readlane_b32 s6, v253, 51
	s_or_b32 s6, s17, s6
	v_cvt_pk_bf16_f32 v124, v124, v125
	v_cvt_pk_bf16_f32 v125, v126, v127
	v_cvt_pk_bf16_f32 v126, v120, v121
	v_cvt_pk_bf16_f32 v127, v122, v123
	s_nop 0
	v_or_b32_e32 v130, s6, v139
	v_readlane_b32 s6, v253, 44
	v_lshlrev_b32_e32 v178, 1, v130
	s_nop 0
	v_add_u32_e32 v131, s6, v138
	v_add_u32_e32 v128, 0x1000, v131
	v_ashrrev_i32_e32 v129, 31, v128
	v_lshlrev_b64 v[128:129], 12, v[128:129]
	v_lshl_add_u64 v[128:129], s[4:5], 0, v[128:129]
	v_lshl_add_u64 v[128:129], v[128:129], 0, v[178:179]
	global_store_dwordx4 v[128:129], v[124:127], off
	v_cvt_pk_bf16_f32 v112, v112, v113
	v_cvt_pk_bf16_f32 v113, v114, v115
	v_cvt_pk_bf16_f32 v114, v104, v105
	v_add_u32_e32 v104, 0x1010, v131
	v_ashrrev_i32_e32 v105, 31, v104
	v_lshlrev_b64 v[104:105], 12, v[104:105]
	v_lshl_add_u64 v[104:105], s[4:5], 0, v[104:105]
	v_cvt_pk_bf16_f32 v115, v106, v107
	global_store_dwordx4 v[128:129], v[112:115], off offset:256
	v_readlane_b32 s6, v255, 8
	s_nop 0
	v_lshl_add_u64 v[112:113], v[104:105], 0, v[178:179]
	v_cvt_pk_bf16_f32 v104, v116, v117
	v_cvt_pk_bf16_f32 v105, v118, v119
	v_cvt_pk_bf16_f32 v106, v108, v109
	v_cvt_pk_bf16_f32 v107, v110, v111
	global_store_dwordx4 v[112:113], v[104:107], off
	v_cvt_pk_bf16_f32 v96, v96, v97
	v_cvt_pk_bf16_f32 v97, v98, v99
	v_cvt_pk_bf16_f32 v98, v88, v89
	v_add_u32_e32 v88, 0x1020, v131
	v_ashrrev_i32_e32 v89, 31, v88
	v_lshlrev_b64 v[88:89], 12, v[88:89]
	v_lshl_add_u64 v[88:89], s[4:5], 0, v[88:89]
	v_cvt_pk_bf16_f32 v99, v90, v91
	global_store_dwordx4 v[112:113], v[96:99], off offset:256
	s_nop 1
	v_lshl_add_u64 v[96:97], v[88:89], 0, v[178:179]
	v_cvt_pk_bf16_f32 v88, v100, v101
	v_cvt_pk_bf16_f32 v89, v102, v103
	v_cvt_pk_bf16_f32 v90, v92, v93
	v_cvt_pk_bf16_f32 v91, v94, v95
	global_store_dwordx4 v[96:97], v[88:91], off
	v_cvt_pk_bf16_f32 v80, v80, v81
	v_cvt_pk_bf16_f32 v81, v82, v83
	v_cvt_pk_bf16_f32 v82, v72, v73
	v_add_u32_e32 v72, 0x1030, v131
	v_ashrrev_i32_e32 v73, 31, v72
	v_lshlrev_b64 v[72:73], 12, v[72:73]
	v_lshl_add_u64 v[72:73], s[4:5], 0, v[72:73]
	v_cvt_pk_bf16_f32 v83, v74, v75
	global_store_dwordx4 v[96:97], v[80:83], off offset:256
	s_nop 1
	v_lshl_add_u64 v[80:81], v[72:73], 0, v[178:179]
	v_cvt_pk_bf16_f32 v72, v84, v85
	v_cvt_pk_bf16_f32 v73, v86, v87
	v_cvt_pk_bf16_f32 v74, v76, v77
	v_cvt_pk_bf16_f32 v75, v78, v79
	global_store_dwordx4 v[80:81], v[72:75], off
	v_cvt_pk_bf16_f32 v68, v68, v69
	v_cvt_pk_bf16_f32 v69, v70, v71
	v_cvt_pk_bf16_f32 v70, v64, v65
	v_add_u32_e32 v64, 0x1080, v131
	v_ashrrev_i32_e32 v65, 31, v64
	v_lshlrev_b64 v[64:65], 12, v[64:65]
	v_lshl_add_u64 v[64:65], s[4:5], 0, v[64:65]
	v_lshl_add_u64 v[64:65], v[64:65], 0, v[178:179]
	v_cvt_pk_bf16_f32 v71, v66, v67
	global_store_dwordx4 v[80:81], v[68:71], off offset:256
	v_cvt_pk_bf16_f32 v60, v60, v61
	v_cvt_pk_bf16_f32 v61, v62, v63
	v_cvt_pk_bf16_f32 v62, v56, v57
	v_cvt_pk_bf16_f32 v63, v58, v59
	global_store_dwordx4 v[64:65], v[60:63], off
	v_cvt_pk_bf16_f32 v48, v48, v49
	v_cvt_pk_bf16_f32 v49, v50, v51
	v_cvt_pk_bf16_f32 v50, v40, v41
	v_add_u32_e32 v40, 0x1090, v131
	v_ashrrev_i32_e32 v41, 31, v40
	v_lshlrev_b64 v[40:41], 12, v[40:41]
	v_lshl_add_u64 v[40:41], s[4:5], 0, v[40:41]
	v_cvt_pk_bf16_f32 v51, v42, v43
	global_store_dwordx4 v[64:65], v[48:51], off offset:256
	s_nop 1
	v_lshl_add_u64 v[48:49], v[40:41], 0, v[178:179]
	v_cvt_pk_bf16_f32 v40, v52, v53
	v_cvt_pk_bf16_f32 v41, v54, v55
	v_cvt_pk_bf16_f32 v42, v44, v45
	v_cvt_pk_bf16_f32 v43, v46, v47
	global_store_dwordx4 v[48:49], v[40:43], off
	v_cvt_pk_bf16_f32 v32, v32, v33
	v_cvt_pk_bf16_f32 v33, v34, v35
	v_cvt_pk_bf16_f32 v34, v24, v25
	v_add_u32_e32 v24, 0x10a0, v131
	v_ashrrev_i32_e32 v25, 31, v24
	v_lshlrev_b64 v[24:25], 12, v[24:25]
	v_lshl_add_u64 v[24:25], s[4:5], 0, v[24:25]
	v_cvt_pk_bf16_f32 v35, v26, v27
	global_store_dwordx4 v[48:49], v[32:35], off offset:256
	s_nop 1
	v_lshl_add_u64 v[32:33], v[24:25], 0, v[178:179]
	v_cvt_pk_bf16_f32 v24, v36, v37
	v_cvt_pk_bf16_f32 v25, v38, v39
	v_cvt_pk_bf16_f32 v26, v28, v29
	v_cvt_pk_bf16_f32 v27, v30, v31
	global_store_dwordx4 v[32:33], v[24:27], off
	v_cvt_pk_bf16_f32 v16, v16, v17
	v_cvt_pk_bf16_f32 v17, v18, v19
	v_cvt_pk_bf16_f32 v18, v8, v9
	v_add_u32_e32 v8, 0x10b0, v131
	v_ashrrev_i32_e32 v9, 31, v8
	v_lshlrev_b64 v[8:9], 12, v[8:9]
	v_lshl_add_u64 v[8:9], s[4:5], 0, v[8:9]
	v_cvt_pk_bf16_f32 v19, v10, v11
	global_store_dwordx4 v[32:33], v[16:19], off offset:256
	s_nop 1
	v_lshl_add_u64 v[16:17], v[8:9], 0, v[178:179]
	v_cvt_pk_bf16_f32 v8, v20, v21
	v_cvt_pk_bf16_f32 v9, v22, v23
	v_cvt_pk_bf16_f32 v10, v12, v13
	v_cvt_pk_bf16_f32 v11, v14, v15
	global_store_dwordx4 v[16:17], v[8:11], off
	v_cvt_pk_bf16_f32 v4, v4, v5
	v_cvt_pk_bf16_f32 v5, v6, v7
	v_cvt_pk_bf16_f32 v6, v0, v1
	v_cvt_pk_bf16_f32 v7, v2, v3
	global_store_dwordx4 v[16:17], v[4:7], off offset:256
	s_waitcnt vmcnt(0)
	s_cmp_lt_u32 s6, 4
	s_cbranch_scc0 .LBB0_938
	s_barrier

.LBB0_943:
	s_add_u32 s12, s10, 0xf3ce0080
	s_addc_u32 s13, s11, -1
	s_cmp_lg_u32 s20, 4
	s_cselect_b32 s12, s12, 0
	s_cselect_b32 s13, s13, 0
	s_add_u32 s14, s6, s12
	s_addc_u32 s15, s7, s13
	s_add_i32 s21, 0, 0x10000
	v_add_u32_e32 v150, s21, v140
	ds_read_b128 v[142:145], v150
	ds_read_b128 v[146:149], v150 offset:1024
	ds_read_b128 v[154:157], v150 offset:2048
	ds_read_b128 v[158:161], v150 offset:3072
	s_add_u32 s12, s8, s12
	s_addc_u32 s13, s9, s13
	v_lshl_add_u64 v[150:151], v[136:137], 0, s[10:11]
	s_add_i32 m0, s22, 0xc000
	ds_read_b128 v[162:165], v141
	ds_read_b128 v[166:169], v141 offset:1024
	ds_read_b128 v[170:173], v141 offset:2048
	ds_read_b128 v[174:177], v141 offset:3072
	ds_read_b128 v[180:183], v141 offset:4096
	ds_read_b128 v[184:187], v141 offset:5120
	ds_read_b128 v[188:191], v141 offset:6144
	ds_read_b128 v[192:195], v141 offset:7168
	global_load_lds_dwordx4 v[150:151], off
	v_lshl_add_u64 v[150:151], v[134:135], 0, s[10:11]
	s_add_i32 m0, s22, 0xe000
	s_nop 0
	global_load_lds_dwordx4 v[150:151], off
	s_waitcnt lgkmcnt(8)
	s_barrier
	s_waitcnt lgkmcnt(0)
	v_mfma_f32_16x16x32_bf16 v[124:127], v[142:145], v[162:165], v[124:127]
	v_mfma_f32_16x16x32_bf16 v[120:123], v[154:157], v[162:165], v[120:123]
	v_mfma_f32_16x16x32_bf16 v[116:119], v[142:145], v[170:173], v[116:119]
	v_mfma_f32_16x16x32_bf16 v[108:111], v[154:157], v[170:173], v[108:111]
	v_mfma_f32_16x16x32_bf16 v[100:103], v[142:145], v[180:183], v[100:103]
	v_mfma_f32_16x16x32_bf16 v[92:95], v[154:157], v[180:183], v[92:95]
	v_mfma_f32_16x16x32_bf16 v[84:87], v[142:145], v[188:191], v[84:87]
	v_mfma_f32_16x16x32_bf16 v[76:79], v[154:157], v[188:191], v[76:79]
	v_mfma_f32_16x16x32_bf16 v[124:127], v[146:149], v[166:169], v[124:127]
	v_mfma_f32_16x16x32_bf16 v[120:123], v[158:161], v[166:169], v[120:123]
	v_mfma_f32_16x16x32_bf16 v[116:119], v[146:149], v[174:177], v[116:119]
	v_mfma_f32_16x16x32_bf16 v[108:111], v[158:161], v[174:177], v[108:111]
	v_mfma_f32_16x16x32_bf16 v[100:103], v[146:149], v[184:187], v[100:103]
	v_mfma_f32_16x16x32_bf16 v[92:95], v[158:161], v[184:187], v[92:95]
	v_mfma_f32_16x16x32_bf16 v[84:87], v[146:149], v[192:195], v[84:87]
	v_mfma_f32_16x16x32_bf16 v[76:79], v[158:161], v[192:195], v[76:79]
	s_barrier
	s_add_i32 s28, 0, 0x14000
	v_add_u32_e32 v150, s28, v140
	s_add_i32 s21, s21, s16
	ds_read_b128 v[196:199], v150
	ds_read_b128 v[224:227], v150 offset:1024
	ds_read_b128 v[228:231], v150 offset:2048
	ds_read_b128 v[232:235], v150 offset:3072
	s_mov_b32 m0, s21
	global_load_lds_dwordx4 v178, s[12:13]
	s_add_i32 m0, s21, 0x2000
	s_nop 0
	global_load_lds_dwordx4 v128, s[12:13]
	s_barrier
	s_waitcnt lgkmcnt(0)
	v_mfma_f32_16x16x32_bf16 v[112:115], v[196:199], v[162:165], v[112:115]
	v_mfma_f32_16x16x32_bf16 v[104:107], v[228:231], v[162:165], v[104:107]
	v_mfma_f32_16x16x32_bf16 v[96:99], v[196:199], v[170:173], v[96:99]
	v_mfma_f32_16x16x32_bf16 v[88:91], v[228:231], v[170:173], v[88:91]
	v_mfma_f32_16x16x32_bf16 v[80:83], v[196:199], v[180:183], v[80:83]
	v_mfma_f32_16x16x32_bf16 v[72:75], v[228:231], v[180:183], v[72:75]
	v_mfma_f32_16x16x32_bf16 v[68:71], v[196:199], v[188:191], v[68:71]
	v_mfma_f32_16x16x32_bf16 v[64:67], v[228:231], v[188:191], v[64:67]
	v_mfma_f32_16x16x32_bf16 v[112:115], v[224:227], v[166:169], v[112:115]
	v_mfma_f32_16x16x32_bf16 v[104:107], v[232:235], v[166:169], v[104:107]
	v_mfma_f32_16x16x32_bf16 v[96:99], v[224:227], v[174:177], v[96:99]
	v_mfma_f32_16x16x32_bf16 v[88:91], v[232:235], v[174:177], v[88:91]
	v_mfma_f32_16x16x32_bf16 v[80:83], v[224:227], v[184:187], v[80:83]
	v_mfma_f32_16x16x32_bf16 v[72:75], v[232:235], v[184:187], v[72:75]
	v_mfma_f32_16x16x32_bf16 v[68:71], v[224:227], v[192:195], v[68:71]
	v_mfma_f32_16x16x32_bf16 v[64:67], v[232:235], v[192:195], v[64:67]
	s_mov_b32 m0, s22
	s_mov_b64 s[100:101], s[14:15]
	s_barrier
	ds_read_b128 v[162:165], v141 offset:16384
	ds_read_b128 v[166:169], v141 offset:17408
	ds_read_b128 v[170:173], v141 offset:18432
	ds_read_b128 v[174:177], v141 offset:19456
	ds_read_b128 v[180:183], v141 offset:20480
	ds_read_b128 v[184:187], v141 offset:21504
	ds_read_b128 v[188:191], v141 offset:22528
	ds_read_b128 v[192:195], v141 offset:23552
	global_load_lds_dwordx4 v132, s[14:15]
	s_mov_b64 s[100:101], s[14:15]
	s_mov_b32 m0, s23
	s_nop 0
	global_load_lds_dwordx4 v130, s[14:15]
	s_barrier
	s_waitcnt lgkmcnt(0)
	v_mfma_f32_16x16x32_bf16 v[60:63], v[142:145], v[162:165], v[60:63]
	v_mfma_f32_16x16x32_bf16 v[56:59], v[154:157], v[162:165], v[56:59]
	v_mfma_f32_16x16x32_bf16 v[52:55], v[142:145], v[170:173], v[52:55]
	v_mfma_f32_16x16x32_bf16 v[44:47], v[154:157], v[170:173], v[44:47]
	v_mfma_f32_16x16x32_bf16 v[36:39], v[142:145], v[180:183], v[36:39]
	v_mfma_f32_16x16x32_bf16 v[28:31], v[154:157], v[180:183], v[28:31]
	v_mfma_f32_16x16x32_bf16 v[20:23], v[142:145], v[188:191], v[20:23]
	v_mfma_f32_16x16x32_bf16 v[12:15], v[154:157], v[188:191], v[12:15]
	v_mfma_f32_16x16x32_bf16 v[60:63], v[146:149], v[166:169], v[60:63]
	v_mfma_f32_16x16x32_bf16 v[56:59], v[158:161], v[166:169], v[56:59]
	v_mfma_f32_16x16x32_bf16 v[52:55], v[146:149], v[174:177], v[52:55]
	v_mfma_f32_16x16x32_bf16 v[44:47], v[158:161], v[174:177], v[44:47]
	v_mfma_f32_16x16x32_bf16 v[36:39], v[146:149], v[184:187], v[36:39]
	v_mfma_f32_16x16x32_bf16 v[28:31], v[158:161], v[184:187], v[28:31]
	v_mfma_f32_16x16x32_bf16 v[20:23], v[146:149], v[192:195], v[20:23]
	v_mfma_f32_16x16x32_bf16 v[12:15], v[158:161], v[192:195], v[12:15]
	s_barrier
	s_add_u32 s26, s12, 0x20000
	s_addc_u32 s27, s13, 0
	s_add_i32 s21, s28, s16
	s_mov_b32 m0, s21
	s_nop 0
	global_load_lds_dwordx4 v178, s[26:27]
	s_add_i32 m0, s21, 0x2000
	s_nop 0
	global_load_lds_dwordx4 v128, s[26:27]
	s_waitcnt vmcnt(6)
	s_barrier
	v_mfma_f32_16x16x32_bf16 v[48:51], v[196:199], v[162:165], v[48:51]
	v_mfma_f32_16x16x32_bf16 v[40:43], v[228:231], v[162:165], v[40:43]
	v_mfma_f32_16x16x32_bf16 v[32:35], v[196:199], v[170:173], v[32:35]
	v_mfma_f32_16x16x32_bf16 v[24:27], v[228:231], v[170:173], v[24:27]
	v_mfma_f32_16x16x32_bf16 v[16:19], v[196:199], v[180:183], v[16:19]
	v_mfma_f32_16x16x32_bf16 v[8:11], v[228:231], v[180:183], v[8:11]
	v_mfma_f32_16x16x32_bf16 v[4:7], v[196:199], v[188:191], v[4:7]
	v_mfma_f32_16x16x32_bf16 v[0:3], v[228:231], v[188:191], v[0:3]
	v_mfma_f32_16x16x32_bf16 v[48:51], v[224:227], v[166:169], v[48:51]
	v_mfma_f32_16x16x32_bf16 v[40:43], v[232:235], v[166:169], v[40:43]
	v_mfma_f32_16x16x32_bf16 v[32:35], v[224:227], v[174:177], v[32:35]
	v_mfma_f32_16x16x32_bf16 v[24:27], v[232:235], v[174:177], v[24:27]
	v_mfma_f32_16x16x32_bf16 v[16:19], v[224:227], v[184:187], v[16:19]
	v_mfma_f32_16x16x32_bf16 v[8:11], v[232:235], v[184:187], v[8:11]
	v_mfma_f32_16x16x32_bf16 v[4:7], v[224:227], v[192:195], v[4:7]
	v_mfma_f32_16x16x32_bf16 v[0:3], v[232:235], v[192:195], v[0:3]
	s_add_i32 s21, 0, 0x18000
	v_add_u32_e32 v153, s21, v140
	s_barrier
	ds_read_b128 v[142:145], v153
	ds_read_b128 v[146:149], v153 offset:1024
	ds_read_b128 v[154:157], v153 offset:2048
	ds_read_b128 v[158:161], v153 offset:3072
	s_add_u32 s14, s14, 0x20000
	s_addc_u32 s15, s15, 0
	s_mov_b32 m0, s24
	ds_read_b128 v[162:165], v141 offset:32768
	ds_read_b128 v[166:169], v141 offset:33792
	ds_read_b128 v[170:173], v141 offset:34816
	ds_read_b128 v[174:177], v141 offset:35840
	ds_read_b128 v[180:183], v141 offset:36864
	ds_read_b128 v[184:187], v141 offset:37888
	ds_read_b128 v[188:191], v141 offset:38912
	ds_read_b128 v[192:195], v141 offset:39936
	global_load_lds_dwordx4 v132, s[14:15]
	s_mov_b32 m0, s25
	s_nop 0
	global_load_lds_dwordx4 v130, s[14:15]
	s_waitcnt lgkmcnt(8)
	s_barrier
	s_waitcnt lgkmcnt(0)
	v_mfma_f32_16x16x32_bf16 v[124:127], v[142:145], v[162:165], v[124:127]
	v_mfma_f32_16x16x32_bf16 v[120:123], v[154:157], v[162:165], v[120:123]
	v_mfma_f32_16x16x32_bf16 v[116:119], v[142:145], v[170:173], v[116:119]
	v_mfma_f32_16x16x32_bf16 v[108:111], v[154:157], v[170:173], v[108:111]
	v_mfma_f32_16x16x32_bf16 v[100:103], v[142:145], v[180:183], v[100:103]
	v_mfma_f32_16x16x32_bf16 v[92:95], v[154:157], v[180:183], v[92:95]
	v_mfma_f32_16x16x32_bf16 v[84:87], v[142:145], v[188:191], v[84:87]
	v_mfma_f32_16x16x32_bf16 v[76:79], v[154:157], v[188:191], v[76:79]
	v_mfma_f32_16x16x32_bf16 v[124:127], v[146:149], v[166:169], v[124:127]
	v_mfma_f32_16x16x32_bf16 v[120:123], v[158:161], v[166:169], v[120:123]
	v_mfma_f32_16x16x32_bf16 v[116:119], v[146:149], v[174:177], v[116:119]
	v_mfma_f32_16x16x32_bf16 v[108:111], v[158:161], v[174:177], v[108:111]
	v_mfma_f32_16x16x32_bf16 v[100:103], v[146:149], v[184:187], v[100:103]
	v_mfma_f32_16x16x32_bf16 v[92:95], v[158:161], v[184:187], v[92:95]
	v_mfma_f32_16x16x32_bf16 v[84:87], v[146:149], v[192:195], v[84:87]
	v_mfma_f32_16x16x32_bf16 v[76:79], v[158:161], v[192:195], v[76:79]
	s_barrier
	s_add_i32 s14, 0, 0x1c000
	s_add_i32 s15, s21, s16
	v_add_u32_e32 v153, s14, v140
	s_add_i32 m0, s15, 0xffffff80
	ds_read_b128 v[196:199], v153
	ds_read_b128 v[224:227], v153 offset:1024
	ds_read_b128 v[228:231], v153 offset:2048
	ds_read_b128 v[232:235], v153 offset:3072
	global_load_lds_dwordx4 v178, s[12:13] offset:128
	s_add_i32 m0, s15, 0x1f80
	s_nop 0
	global_load_lds_dwordx4 v128, s[12:13] offset:128
	s_barrier
	s_waitcnt lgkmcnt(0)
	v_mfma_f32_16x16x32_bf16 v[112:115], v[196:199], v[162:165], v[112:115]
	v_mfma_f32_16x16x32_bf16 v[104:107], v[228:231], v[162:165], v[104:107]
	v_mfma_f32_16x16x32_bf16 v[96:99], v[196:199], v[170:173], v[96:99]
	v_mfma_f32_16x16x32_bf16 v[88:91], v[228:231], v[170:173], v[88:91]
	v_mfma_f32_16x16x32_bf16 v[80:83], v[196:199], v[180:183], v[80:83]
	v_mfma_f32_16x16x32_bf16 v[72:75], v[228:231], v[180:183], v[72:75]
	v_mfma_f32_16x16x32_bf16 v[68:71], v[196:199], v[188:191], v[68:71]
	v_mfma_f32_16x16x32_bf16 v[64:67], v[228:231], v[188:191], v[64:67]
	v_mfma_f32_16x16x32_bf16 v[112:115], v[224:227], v[166:169], v[112:115]
	v_mfma_f32_16x16x32_bf16 v[104:107], v[232:235], v[166:169], v[104:107]
	v_mfma_f32_16x16x32_bf16 v[96:99], v[224:227], v[174:177], v[96:99]
	v_mfma_f32_16x16x32_bf16 v[88:91], v[232:235], v[174:177], v[88:91]
	v_mfma_f32_16x16x32_bf16 v[80:83], v[224:227], v[184:187], v[80:83]
	v_mfma_f32_16x16x32_bf16 v[72:75], v[232:235], v[184:187], v[72:75]
	v_mfma_f32_16x16x32_bf16 v[68:71], v[224:227], v[192:195], v[68:71]
	v_mfma_f32_16x16x32_bf16 v[64:67], v[232:235], v[192:195], v[64:67]
	s_add_i32 m0, s18, 0xffffff80
	s_barrier
	ds_read_b128 v[162:165], v141 offset:49152
	ds_read_b128 v[166:169], v141 offset:50176
	ds_read_b128 v[170:173], v141 offset:51200
	ds_read_b128 v[174:177], v141 offset:52224
	ds_read_b128 v[180:183], v141 offset:53248
	ds_read_b128 v[184:187], v141 offset:54272
	ds_read_b128 v[188:191], v141 offset:55296
	ds_read_b128 v[192:195], v141 offset:56320
	global_load_lds_dwordx4 v132, s[100:101] offset:128
	s_add_i32 m0, s19, 0xffffff80
	s_nop 0
	global_load_lds_dwordx4 v130, s[100:101] offset:128
	s_barrier
	s_waitcnt lgkmcnt(0)
	v_mfma_f32_16x16x32_bf16 v[60:63], v[142:145], v[162:165], v[60:63]
	v_mfma_f32_16x16x32_bf16 v[56:59], v[154:157], v[162:165], v[56:59]
	v_mfma_f32_16x16x32_bf16 v[52:55], v[142:145], v[170:173], v[52:55]
	v_mfma_f32_16x16x32_bf16 v[44:47], v[154:157], v[170:173], v[44:47]
	v_mfma_f32_16x16x32_bf16 v[36:39], v[142:145], v[180:183], v[36:39]
	v_mfma_f32_16x16x32_bf16 v[28:31], v[154:157], v[180:183], v[28:31]
	v_mfma_f32_16x16x32_bf16 v[20:23], v[142:145], v[188:191], v[20:23]
	v_mfma_f32_16x16x32_bf16 v[12:15], v[154:157], v[188:191], v[12:15]
	v_mfma_f32_16x16x32_bf16 v[60:63], v[146:149], v[166:169], v[60:63]
	v_mfma_f32_16x16x32_bf16 v[56:59], v[158:161], v[166:169], v[56:59]
	v_mfma_f32_16x16x32_bf16 v[52:55], v[146:149], v[174:177], v[52:55]
	v_mfma_f32_16x16x32_bf16 v[44:47], v[158:161], v[174:177], v[44:47]
	v_mfma_f32_16x16x32_bf16 v[36:39], v[146:149], v[184:187], v[36:39]
	v_mfma_f32_16x16x32_bf16 v[28:31], v[158:161], v[184:187], v[28:31]
	v_mfma_f32_16x16x32_bf16 v[20:23], v[146:149], v[192:195], v[20:23]
	v_mfma_f32_16x16x32_bf16 v[12:15], v[158:161], v[192:195], v[12:15]
	s_barrier
	s_add_u32 s12, s12, 0x20080
	s_addc_u32 s13, s13, 0
	s_add_i32 s14, s14, s16
	s_mov_b32 m0, s14
	s_nop 0
	global_load_lds_dwordx4 v178, s[12:13]
	s_add_i32 m0, s14, 0x2000
	s_nop 0
	global_load_lds_dwordx4 v128, s[12:13]
	s_waitcnt vmcnt(6)
	s_barrier
	v_mfma_f32_16x16x32_bf16 v[48:51], v[196:199], v[162:165], v[48:51]
	v_mfma_f32_16x16x32_bf16 v[40:43], v[228:231], v[162:165], v[40:43]
	v_mfma_f32_16x16x32_bf16 v[32:35], v[196:199], v[170:173], v[32:35]
	v_mfma_f32_16x16x32_bf16 v[24:27], v[228:231], v[170:173], v[24:27]
	v_mfma_f32_16x16x32_bf16 v[16:19], v[196:199], v[180:183], v[16:19]
	v_mfma_f32_16x16x32_bf16 v[8:11], v[228:231], v[180:183], v[8:11]
	v_mfma_f32_16x16x32_bf16 v[4:7], v[196:199], v[188:191], v[4:7]
	v_mfma_f32_16x16x32_bf16 v[0:3], v[228:231], v[188:191], v[0:3]
	v_mfma_f32_16x16x32_bf16 v[48:51], v[224:227], v[166:169], v[48:51]
	v_mfma_f32_16x16x32_bf16 v[40:43], v[232:235], v[166:169], v[40:43]
	v_mfma_f32_16x16x32_bf16 v[32:35], v[224:227], v[174:177], v[32:35]
	v_mfma_f32_16x16x32_bf16 v[24:27], v[232:235], v[174:177], v[24:27]
	v_mfma_f32_16x16x32_bf16 v[16:19], v[224:227], v[184:187], v[16:19]
	v_mfma_f32_16x16x32_bf16 v[8:11], v[232:235], v[184:187], v[8:11]
	v_mfma_f32_16x16x32_bf16 v[4:7], v[224:227], v[192:195], v[4:7]
	v_mfma_f32_16x16x32_bf16 v[0:3], v[232:235], v[192:195], v[0:3]
	s_add_i32 s20, s20, 2
	s_add_u32 s10, s10, 0x100
	s_addc_u32 s11, s11, 0
	s_cmp_gt_u32 s20, 5
	s_barrier
	s_cbranch_scc0 .LBB0_943
	v_readlane_b32 s6, v254, 23
	s_or_b32 s6, s17, s6
	v_cvt_pk_bf16_f32 v124, v124, v125
	v_cvt_pk_bf16_f32 v125, v126, v127
	v_cvt_pk_bf16_f32 v126, v120, v121
	v_cvt_pk_bf16_f32 v127, v122, v123
	s_nop 0
	v_or_b32_e32 v132, s6, v139
	v_readlane_b32 s6, v254, 25
	v_lshlrev_b32_e32 v178, 1, v132
	s_nop 0
	v_add_u32_e32 v128, s6, v138
	v_ashrrev_i32_e32 v129, 31, v128
	v_lshlrev_b64 v[130:131], 12, v[128:129]
	v_lshl_add_u64 v[130:131], s[4:5], 0, v[130:131]
	v_lshl_add_u64 v[130:131], v[130:131], 0, v[178:179]
	global_store_dwordx4 v[130:131], v[124:127], off
	v_cvt_pk_bf16_f32 v112, v112, v113
	v_cvt_pk_bf16_f32 v113, v114, v115
	v_cvt_pk_bf16_f32 v114, v104, v105
	v_or_b32_e32 v104, 16, v128
	v_ashrrev_i32_e32 v105, 31, v104
	v_lshlrev_b64 v[104:105], 12, v[104:105]
	v_lshl_add_u64 v[104:105], s[4:5], 0, v[104:105]
	v_cvt_pk_bf16_f32 v115, v106, v107
	global_store_dwordx4 v[130:131], v[112:115], off offset:256
	s_nop 1
	v_lshl_add_u64 v[112:113], v[104:105], 0, v[178:179]
	v_cvt_pk_bf16_f32 v104, v116, v117
	v_cvt_pk_bf16_f32 v105, v118, v119
	v_cvt_pk_bf16_f32 v106, v108, v109
	v_cvt_pk_bf16_f32 v107, v110, v111
	global_store_dwordx4 v[112:113], v[104:107], off
	v_cvt_pk_bf16_f32 v96, v96, v97
	v_cvt_pk_bf16_f32 v97, v98, v99
	v_cvt_pk_bf16_f32 v98, v88, v89
	v_or_b32_e32 v88, 32, v128
	v_ashrrev_i32_e32 v89, 31, v88
	v_lshlrev_b64 v[88:89], 12, v[88:89]
	v_lshl_add_u64 v[88:89], s[4:5], 0, v[88:89]
	v_cvt_pk_bf16_f32 v99, v90, v91
	global_store_dwordx4 v[112:113], v[96:99], off offset:256
	s_nop 1
	v_lshl_add_u64 v[96:97], v[88:89], 0, v[178:179]
	v_cvt_pk_bf16_f32 v88, v100, v101
	v_cvt_pk_bf16_f32 v89, v102, v103
	v_cvt_pk_bf16_f32 v90, v92, v93
	v_cvt_pk_bf16_f32 v91, v94, v95
	global_store_dwordx4 v[96:97], v[88:91], off
	v_cvt_pk_bf16_f32 v80, v80, v81
	v_cvt_pk_bf16_f32 v81, v82, v83
	v_cvt_pk_bf16_f32 v82, v72, v73
	v_or_b32_e32 v72, 48, v128
	v_ashrrev_i32_e32 v73, 31, v72
	v_lshlrev_b64 v[72:73], 12, v[72:73]
	v_lshl_add_u64 v[72:73], s[4:5], 0, v[72:73]
	v_cvt_pk_bf16_f32 v83, v74, v75
	global_store_dwordx4 v[96:97], v[80:83], off offset:256
	s_nop 1
	v_lshl_add_u64 v[80:81], v[72:73], 0, v[178:179]
	v_cvt_pk_bf16_f32 v72, v84, v85
	v_cvt_pk_bf16_f32 v73, v86, v87
	v_cvt_pk_bf16_f32 v74, v76, v77
	v_cvt_pk_bf16_f32 v75, v78, v79
	global_store_dwordx4 v[80:81], v[72:75], off
	v_cvt_pk_bf16_f32 v68, v68, v69
	v_cvt_pk_bf16_f32 v69, v70, v71
	v_cvt_pk_bf16_f32 v70, v64, v65
	v_add_u32_e32 v64, 0x80, v128
	v_ashrrev_i32_e32 v65, 31, v64
	v_lshlrev_b64 v[64:65], 12, v[64:65]
	v_lshl_add_u64 v[64:65], s[4:5], 0, v[64:65]
	v_lshl_add_u64 v[64:65], v[64:65], 0, v[178:179]
	v_cvt_pk_bf16_f32 v71, v66, v67
	global_store_dwordx4 v[80:81], v[68:71], off offset:256
	v_cvt_pk_bf16_f32 v60, v60, v61
	v_cvt_pk_bf16_f32 v61, v62, v63
	v_cvt_pk_bf16_f32 v62, v56, v57
	v_cvt_pk_bf16_f32 v63, v58, v59
	global_store_dwordx4 v[64:65], v[60:63], off
	v_cvt_pk_bf16_f32 v48, v48, v49
	v_cvt_pk_bf16_f32 v49, v50, v51
	v_cvt_pk_bf16_f32 v50, v40, v41
	v_add_u32_e32 v40, 0x90, v128
	v_ashrrev_i32_e32 v41, 31, v40
	v_lshlrev_b64 v[40:41], 12, v[40:41]
	v_lshl_add_u64 v[40:41], s[4:5], 0, v[40:41]
	v_cvt_pk_bf16_f32 v51, v42, v43
	global_store_dwordx4 v[64:65], v[48:51], off offset:256
	s_nop 1
	v_lshl_add_u64 v[48:49], v[40:41], 0, v[178:179]
	v_cvt_pk_bf16_f32 v40, v52, v53
	v_cvt_pk_bf16_f32 v41, v54, v55
	v_cvt_pk_bf16_f32 v42, v44, v45
	v_cvt_pk_bf16_f32 v43, v46, v47
	global_store_dwordx4 v[48:49], v[40:43], off
	v_cvt_pk_bf16_f32 v32, v32, v33
	v_cvt_pk_bf16_f32 v33, v34, v35
	v_cvt_pk_bf16_f32 v34, v24, v25
	v_add_u32_e32 v24, 0xa0, v128
	v_ashrrev_i32_e32 v25, 31, v24
	v_lshlrev_b64 v[24:25], 12, v[24:25]
	v_lshl_add_u64 v[24:25], s[4:5], 0, v[24:25]
	v_cvt_pk_bf16_f32 v35, v26, v27
	global_store_dwordx4 v[48:49], v[32:35], off offset:256
	s_nop 1
	v_lshl_add_u64 v[32:33], v[24:25], 0, v[178:179]
	v_cvt_pk_bf16_f32 v24, v36, v37
	v_cvt_pk_bf16_f32 v25, v38, v39
	v_cvt_pk_bf16_f32 v26, v28, v29
	v_cvt_pk_bf16_f32 v27, v30, v31
	global_store_dwordx4 v[32:33], v[24:27], off
	v_cvt_pk_bf16_f32 v16, v16, v17
	v_cvt_pk_bf16_f32 v17, v18, v19
	v_cvt_pk_bf16_f32 v18, v8, v9
	v_add_u32_e32 v8, 0xb0, v128
	v_ashrrev_i32_e32 v9, 31, v8
	v_lshlrev_b64 v[8:9], 12, v[8:9]
	v_lshl_add_u64 v[8:9], s[4:5], 0, v[8:9]
	v_cvt_pk_bf16_f32 v19, v10, v11
	global_store_dwordx4 v[32:33], v[16:19], off offset:256
	v_readlane_b32 s4, v255, 8
	s_nop 0
	v_lshl_add_u64 v[16:17], v[8:9], 0, v[178:179]
	v_cvt_pk_bf16_f32 v8, v20, v21
	v_cvt_pk_bf16_f32 v9, v22, v23
	v_cvt_pk_bf16_f32 v10, v12, v13
	v_cvt_pk_bf16_f32 v11, v14, v15
	global_store_dwordx4 v[16:17], v[8:11], off
	v_cvt_pk_bf16_f32 v4, v4, v5
	v_cvt_pk_bf16_f32 v5, v6, v7
	v_cvt_pk_bf16_f32 v6, v0, v1
	v_cvt_pk_bf16_f32 v7, v2, v3
	global_store_dwordx4 v[16:17], v[4:7], off offset:256
	s_waitcnt vmcnt(0)
	s_cmp_lt_u32 s4, 4
	s_cbranch_scc0 .LBB0_946
	s_barrier

.LBB0_1077:
	s_add_u32 s18, s16, 0x100
	s_addc_u32 s19, s17, 0
	s_add_i32 s66, 0, 0x10000
	v_add_u32_e32 v140, s66, v157
	ds_read_b128 v[128:131], v140
	ds_read_b128 v[132:135], v140 offset:1024
	ds_read_b128 v[136:139], v140 offset:2048
	ds_read_b128 v[140:143], v140 offset:3072
	s_cmp_eq_u32 s63, 28
	s_cselect_b32 s23, s13, s19
	s_cselect_b32 s22, s12, s18
	s_cselect_b32 s21, s15, s62
	s_cselect_b32 s20, s14, s5
	v_lshl_add_u64 v[154:155], s[16:17], 0, v[148:149]
	s_add_i32 m0, s29, 0xc000
	ds_read_b128 v[150:153], v159
	ds_read_b128 v[160:163], v159 offset:1024
	ds_read_b128 v[164:167], v159 offset:2048
	ds_read_b128 v[168:171], v159 offset:3072
	ds_read_b128 v[172:175], v159 offset:4096
	ds_read_b128 v[180:183], v159 offset:5120
	ds_read_b128 v[184:187], v159 offset:6144
	ds_read_b128 v[188:191], v159 offset:7168
	global_load_lds_dwordx4 v[154:155], off
	v_lshl_add_u64 v[154:155], s[16:17], 0, v[146:147]
	s_add_i32 m0, s29, 0xe000
	s_nop 0
	global_load_lds_dwordx4 v[154:155], off
	s_waitcnt lgkmcnt(8)
	s_barrier
	s_waitcnt lgkmcnt(0)
	v_mfma_f32_16x16x32_bf16 v[124:127], v[128:131], v[150:153], v[124:127]
	v_mfma_f32_16x16x32_bf16 v[120:123], v[136:139], v[150:153], v[120:123]
	v_mfma_f32_16x16x32_bf16 v[108:111], v[128:131], v[164:167], v[108:111]
	v_mfma_f32_16x16x32_bf16 v[104:107], v[136:139], v[164:167], v[104:107]
	v_mfma_f32_16x16x32_bf16 v[92:95], v[128:131], v[172:175], v[92:95]
	v_mfma_f32_16x16x32_bf16 v[88:91], v[136:139], v[172:175], v[88:91]
	v_mfma_f32_16x16x32_bf16 v[76:79], v[128:131], v[184:187], v[76:79]
	v_mfma_f32_16x16x32_bf16 v[72:75], v[136:139], v[184:187], v[72:75]
	v_mfma_f32_16x16x32_bf16 v[124:127], v[132:135], v[160:163], v[124:127]
	v_mfma_f32_16x16x32_bf16 v[120:123], v[140:143], v[160:163], v[120:123]
	v_mfma_f32_16x16x32_bf16 v[108:111], v[132:135], v[168:171], v[108:111]
	v_mfma_f32_16x16x32_bf16 v[104:107], v[140:143], v[168:171], v[104:107]
	v_mfma_f32_16x16x32_bf16 v[92:95], v[132:135], v[180:183], v[92:95]
	v_mfma_f32_16x16x32_bf16 v[88:91], v[140:143], v[180:183], v[88:91]
	v_mfma_f32_16x16x32_bf16 v[76:79], v[132:135], v[188:191], v[76:79]
	v_mfma_f32_16x16x32_bf16 v[72:75], v[140:143], v[188:191], v[72:75]
	s_barrier
	s_add_i32 s67, 0, 0x14000
	v_add_u32_e32 v154, s67, v157
	s_add_i32 s16, s66, s28
	ds_read_b128 v[192:195], v154
	ds_read_b128 v[196:199], v154 offset:1024
	ds_read_b128 v[204:207], v154 offset:2048
	ds_read_b128 v[212:215], v154 offset:3072
	s_mov_b32 m0, s16
	global_load_lds_dwordx4 v178, s[20:21]
	s_add_i32 m0, s16, 0x2000
	s_nop 0
	global_load_lds_dwordx4 v144, s[20:21]
	s_barrier
	s_waitcnt lgkmcnt(0)
	v_mfma_f32_16x16x32_bf16 v[116:119], v[192:195], v[150:153], v[116:119]
	v_mfma_f32_16x16x32_bf16 v[112:115], v[204:207], v[150:153], v[112:115]
	v_mfma_f32_16x16x32_bf16 v[100:103], v[192:195], v[164:167], v[100:103]
	v_mfma_f32_16x16x32_bf16 v[96:99], v[204:207], v[164:167], v[96:99]
	v_mfma_f32_16x16x32_bf16 v[84:87], v[192:195], v[172:175], v[84:87]
	v_mfma_f32_16x16x32_bf16 v[80:83], v[204:207], v[172:175], v[80:83]
	v_mfma_f32_16x16x32_bf16 v[68:71], v[192:195], v[184:187], v[68:71]
	v_mfma_f32_16x16x32_bf16 v[64:67], v[204:207], v[184:187], v[64:67]
	v_mfma_f32_16x16x32_bf16 v[116:119], v[196:199], v[160:163], v[116:119]
	v_mfma_f32_16x16x32_bf16 v[112:115], v[212:215], v[160:163], v[112:115]
	v_mfma_f32_16x16x32_bf16 v[100:103], v[196:199], v[168:171], v[100:103]
	v_mfma_f32_16x16x32_bf16 v[96:99], v[212:215], v[168:171], v[96:99]
	v_mfma_f32_16x16x32_bf16 v[84:87], v[196:199], v[180:183], v[84:87]
	v_mfma_f32_16x16x32_bf16 v[80:83], v[212:215], v[180:183], v[80:83]
	v_mfma_f32_16x16x32_bf16 v[68:71], v[196:199], v[188:191], v[68:71]
	v_mfma_f32_16x16x32_bf16 v[64:67], v[212:215], v[188:191], v[64:67]
	s_mov_b32 m0, s29
	s_mov_b64 s[100:101], s[22:23]
	s_barrier
	ds_read_b128 v[150:153], v159 offset:16384
	ds_read_b128 v[160:163], v159 offset:17408
	ds_read_b128 v[164:167], v159 offset:18432
	ds_read_b128 v[168:171], v159 offset:19456
	ds_read_b128 v[172:175], v159 offset:20480
	ds_read_b128 v[180:183], v159 offset:21504
	ds_read_b128 v[184:187], v159 offset:22528
	ds_read_b128 v[188:191], v159 offset:23552
	global_load_lds_dwordx4 v178, s[22:23]
	s_mov_b64 s[100:101], s[22:23]
	s_mov_b32 m0, s30
	s_nop 0
	global_load_lds_dwordx4 v144, s[22:23]
	s_barrier
	s_waitcnt lgkmcnt(0)
	v_mfma_f32_16x16x32_bf16 v[60:63], v[128:131], v[150:153], v[60:63]
	v_mfma_f32_16x16x32_bf16 v[56:59], v[136:139], v[150:153], v[56:59]
	v_mfma_f32_16x16x32_bf16 v[44:47], v[128:131], v[164:167], v[44:47]
	v_mfma_f32_16x16x32_bf16 v[40:43], v[136:139], v[164:167], v[40:43]
	v_mfma_f32_16x16x32_bf16 v[28:31], v[128:131], v[172:175], v[28:31]
	v_mfma_f32_16x16x32_bf16 v[24:27], v[136:139], v[172:175], v[24:27]
	v_mfma_f32_16x16x32_bf16 v[12:15], v[128:131], v[184:187], v[12:15]
	v_mfma_f32_16x16x32_bf16 v[8:11], v[136:139], v[184:187], v[8:11]
	v_mfma_f32_16x16x32_bf16 v[60:63], v[132:135], v[160:163], v[60:63]
	v_mfma_f32_16x16x32_bf16 v[56:59], v[140:143], v[160:163], v[56:59]
	v_mfma_f32_16x16x32_bf16 v[44:47], v[132:135], v[168:171], v[44:47]
	v_mfma_f32_16x16x32_bf16 v[40:43], v[140:143], v[168:171], v[40:43]
	v_mfma_f32_16x16x32_bf16 v[28:31], v[132:135], v[180:183], v[28:31]
	v_mfma_f32_16x16x32_bf16 v[24:27], v[140:143], v[180:183], v[24:27]
	v_mfma_f32_16x16x32_bf16 v[12:15], v[132:135], v[188:191], v[12:15]
	v_mfma_f32_16x16x32_bf16 v[8:11], v[140:143], v[188:191], v[8:11]
	s_barrier
	s_add_u32 s16, s20, 0x80000
	s_addc_u32 s17, s21, 0
	s_add_i32 s66, s67, s28
	s_mov_b32 m0, s66
	s_nop 0
	global_load_lds_dwordx4 v178, s[16:17]
	s_add_i32 m0, s66, 0x2000
	s_nop 0
	global_load_lds_dwordx4 v144, s[16:17]
	s_waitcnt vmcnt(6)
	s_barrier
	v_mfma_f32_16x16x32_bf16 v[52:55], v[192:195], v[150:153], v[52:55]
	v_mfma_f32_16x16x32_bf16 v[48:51], v[204:207], v[150:153], v[48:51]
	v_mfma_f32_16x16x32_bf16 v[36:39], v[192:195], v[164:167], v[36:39]
	v_mfma_f32_16x16x32_bf16 v[32:35], v[204:207], v[164:167], v[32:35]
	v_mfma_f32_16x16x32_bf16 v[20:23], v[192:195], v[172:175], v[20:23]
	v_mfma_f32_16x16x32_bf16 v[16:19], v[204:207], v[172:175], v[16:19]
	v_mfma_f32_16x16x32_bf16 v[4:7], v[192:195], v[184:187], v[4:7]
	v_mfma_f32_16x16x32_bf16 v[0:3], v[204:207], v[184:187], v[0:3]
	v_mfma_f32_16x16x32_bf16 v[52:55], v[196:199], v[160:163], v[52:55]
	v_mfma_f32_16x16x32_bf16 v[48:51], v[212:215], v[160:163], v[48:51]
	v_mfma_f32_16x16x32_bf16 v[36:39], v[196:199], v[168:171], v[36:39]
	v_mfma_f32_16x16x32_bf16 v[32:35], v[212:215], v[168:171], v[32:35]
	v_mfma_f32_16x16x32_bf16 v[20:23], v[196:199], v[180:183], v[20:23]
	v_mfma_f32_16x16x32_bf16 v[16:19], v[212:215], v[180:183], v[16:19]
	v_mfma_f32_16x16x32_bf16 v[4:7], v[196:199], v[188:191], v[4:7]
	v_mfma_f32_16x16x32_bf16 v[0:3], v[212:215], v[188:191], v[0:3]
	s_add_i32 s66, 0, 0x18000
	v_add_u32_e32 v140, s66, v157
	s_barrier
	ds_read_b128 v[128:131], v140
	ds_read_b128 v[132:135], v140 offset:1024
	ds_read_b128 v[136:139], v140 offset:2048
	ds_read_b128 v[140:143], v140 offset:3072
	s_add_u32 s16, s22, 0x80000
	s_addc_u32 s17, s23, 0
	s_mov_b32 m0, s31
	ds_read_b128 v[150:153], v159 offset:32768
	ds_read_b128 v[160:163], v159 offset:33792
	ds_read_b128 v[164:167], v159 offset:34816
	ds_read_b128 v[168:171], v159 offset:35840
	ds_read_b128 v[172:175], v159 offset:36864
	ds_read_b128 v[180:183], v159 offset:37888
	ds_read_b128 v[184:187], v159 offset:38912
	ds_read_b128 v[188:191], v159 offset:39936
	global_load_lds_dwordx4 v178, s[16:17]
	s_mov_b32 m0, s34
	s_nop 0
	global_load_lds_dwordx4 v144, s[16:17]
	s_waitcnt lgkmcnt(8)
	s_barrier
	s_waitcnt lgkmcnt(0)
	v_mfma_f32_16x16x32_bf16 v[124:127], v[128:131], v[150:153], v[124:127]
	v_mfma_f32_16x16x32_bf16 v[120:123], v[136:139], v[150:153], v[120:123]
	v_mfma_f32_16x16x32_bf16 v[108:111], v[128:131], v[164:167], v[108:111]
	v_mfma_f32_16x16x32_bf16 v[104:107], v[136:139], v[164:167], v[104:107]
	v_mfma_f32_16x16x32_bf16 v[92:95], v[128:131], v[172:175], v[92:95]
	v_mfma_f32_16x16x32_bf16 v[88:91], v[136:139], v[172:175], v[88:91]
	v_mfma_f32_16x16x32_bf16 v[76:79], v[128:131], v[184:187], v[76:79]
	v_mfma_f32_16x16x32_bf16 v[72:75], v[136:139], v[184:187], v[72:75]
	v_mfma_f32_16x16x32_bf16 v[124:127], v[132:135], v[160:163], v[124:127]
	v_mfma_f32_16x16x32_bf16 v[120:123], v[140:143], v[160:163], v[120:123]
	v_mfma_f32_16x16x32_bf16 v[108:111], v[132:135], v[168:171], v[108:111]
	v_mfma_f32_16x16x32_bf16 v[104:107], v[140:143], v[168:171], v[104:107]
	v_mfma_f32_16x16x32_bf16 v[92:95], v[132:135], v[180:183], v[92:95]
	v_mfma_f32_16x16x32_bf16 v[88:91], v[140:143], v[180:183], v[88:91]
	v_mfma_f32_16x16x32_bf16 v[76:79], v[132:135], v[188:191], v[76:79]
	v_mfma_f32_16x16x32_bf16 v[72:75], v[140:143], v[188:191], v[72:75]
	s_barrier
	s_add_i32 s22, 0, 0x1c000
	s_add_i32 s16, s66, s28
	v_add_u32_e32 v212, s22, v157
	s_add_i32 m0, s16, 0xffffff80
	ds_read_b128 v[192:195], v212
	ds_read_b128 v[196:199], v212 offset:1024
	ds_read_b128 v[204:207], v212 offset:2048
	ds_read_b128 v[212:215], v212 offset:3072
	global_load_lds_dwordx4 v178, s[20:21] offset:128
	s_add_i32 m0, s16, 0x1f80
	s_nop 0
	global_load_lds_dwordx4 v144, s[20:21] offset:128
	s_barrier
	s_waitcnt lgkmcnt(0)
	v_mfma_f32_16x16x32_bf16 v[116:119], v[192:195], v[150:153], v[116:119]
	v_mfma_f32_16x16x32_bf16 v[112:115], v[204:207], v[150:153], v[112:115]
	v_mfma_f32_16x16x32_bf16 v[100:103], v[192:195], v[164:167], v[100:103]
	v_mfma_f32_16x16x32_bf16 v[96:99], v[204:207], v[164:167], v[96:99]
	v_mfma_f32_16x16x32_bf16 v[84:87], v[192:195], v[172:175], v[84:87]
	v_mfma_f32_16x16x32_bf16 v[80:83], v[204:207], v[172:175], v[80:83]
	v_mfma_f32_16x16x32_bf16 v[68:71], v[192:195], v[184:187], v[68:71]
	v_mfma_f32_16x16x32_bf16 v[64:67], v[204:207], v[184:187], v[64:67]
	v_mfma_f32_16x16x32_bf16 v[116:119], v[196:199], v[160:163], v[116:119]
	v_mfma_f32_16x16x32_bf16 v[112:115], v[212:215], v[160:163], v[112:115]
	v_mfma_f32_16x16x32_bf16 v[100:103], v[196:199], v[168:171], v[100:103]
	v_mfma_f32_16x16x32_bf16 v[96:99], v[212:215], v[168:171], v[96:99]
	v_mfma_f32_16x16x32_bf16 v[84:87], v[196:199], v[180:183], v[84:87]
	v_mfma_f32_16x16x32_bf16 v[80:83], v[212:215], v[180:183], v[80:83]
	v_mfma_f32_16x16x32_bf16 v[68:71], v[196:199], v[188:191], v[68:71]
	v_mfma_f32_16x16x32_bf16 v[64:67], v[212:215], v[188:191], v[64:67]
	s_add_i32 m0, s56, 0xffffff80
	s_barrier
	ds_read_b128 v[150:153], v159 offset:49152
	ds_read_b128 v[160:163], v159 offset:50176
	ds_read_b128 v[164:167], v159 offset:51200
	ds_read_b128 v[168:171], v159 offset:52224
	ds_read_b128 v[172:175], v159 offset:53248
	ds_read_b128 v[180:183], v159 offset:54272
	ds_read_b128 v[184:187], v159 offset:55296
	ds_read_b128 v[188:191], v159 offset:56320
	global_load_lds_dwordx4 v178, s[100:101] offset:128
	s_add_i32 m0, s57, 0xffffff80
	s_nop 0
	global_load_lds_dwordx4 v144, s[100:101] offset:128
	s_barrier
	s_waitcnt lgkmcnt(0)
	v_mfma_f32_16x16x32_bf16 v[60:63], v[128:131], v[150:153], v[60:63]
	v_mfma_f32_16x16x32_bf16 v[56:59], v[136:139], v[150:153], v[56:59]
	v_mfma_f32_16x16x32_bf16 v[44:47], v[128:131], v[164:167], v[44:47]
	v_mfma_f32_16x16x32_bf16 v[40:43], v[136:139], v[164:167], v[40:43]
	v_mfma_f32_16x16x32_bf16 v[28:31], v[128:131], v[172:175], v[28:31]
	v_mfma_f32_16x16x32_bf16 v[24:27], v[136:139], v[172:175], v[24:27]
	v_mfma_f32_16x16x32_bf16 v[12:15], v[128:131], v[184:187], v[12:15]
	v_mfma_f32_16x16x32_bf16 v[8:11], v[136:139], v[184:187], v[8:11]
	v_mfma_f32_16x16x32_bf16 v[60:63], v[132:135], v[160:163], v[60:63]
	v_mfma_f32_16x16x32_bf16 v[56:59], v[140:143], v[160:163], v[56:59]
	v_mfma_f32_16x16x32_bf16 v[44:47], v[132:135], v[168:171], v[44:47]
	v_mfma_f32_16x16x32_bf16 v[40:43], v[140:143], v[168:171], v[40:43]
	v_mfma_f32_16x16x32_bf16 v[28:31], v[132:135], v[180:183], v[28:31]
	v_mfma_f32_16x16x32_bf16 v[24:27], v[140:143], v[180:183], v[24:27]
	v_mfma_f32_16x16x32_bf16 v[12:15], v[132:135], v[188:191], v[12:15]
	v_mfma_f32_16x16x32_bf16 v[8:11], v[140:143], v[188:191], v[8:11]
	s_barrier
	s_add_u32 s16, s20, 0x80080
	s_addc_u32 s17, s21, 0
	s_add_i32 s20, s22, s28
	s_mov_b32 m0, s20
	s_nop 0
	global_load_lds_dwordx4 v178, s[16:17]
	s_add_i32 m0, s20, 0x2000
	s_nop 0
	global_load_lds_dwordx4 v144, s[16:17]
	s_waitcnt vmcnt(6)
	s_barrier
	v_mfma_f32_16x16x32_bf16 v[52:55], v[192:195], v[150:153], v[52:55]
	v_mfma_f32_16x16x32_bf16 v[48:51], v[204:207], v[150:153], v[48:51]
	v_mfma_f32_16x16x32_bf16 v[36:39], v[192:195], v[164:167], v[36:39]
	v_mfma_f32_16x16x32_bf16 v[32:35], v[204:207], v[164:167], v[32:35]
	v_mfma_f32_16x16x32_bf16 v[20:23], v[192:195], v[172:175], v[20:23]
	v_mfma_f32_16x16x32_bf16 v[16:19], v[204:207], v[172:175], v[16:19]
	v_mfma_f32_16x16x32_bf16 v[4:7], v[192:195], v[184:187], v[4:7]
	v_mfma_f32_16x16x32_bf16 v[0:3], v[204:207], v[184:187], v[0:3]
	v_mfma_f32_16x16x32_bf16 v[52:55], v[196:199], v[160:163], v[52:55]
	v_mfma_f32_16x16x32_bf16 v[48:51], v[212:215], v[160:163], v[48:51]
	v_mfma_f32_16x16x32_bf16 v[36:39], v[196:199], v[168:171], v[36:39]
	v_mfma_f32_16x16x32_bf16 v[32:35], v[212:215], v[168:171], v[32:35]
	v_mfma_f32_16x16x32_bf16 v[20:23], v[196:199], v[180:183], v[20:23]
	v_mfma_f32_16x16x32_bf16 v[16:19], v[212:215], v[180:183], v[16:19]
	v_mfma_f32_16x16x32_bf16 v[4:7], v[196:199], v[188:191], v[4:7]
	v_mfma_f32_16x16x32_bf16 v[0:3], v[212:215], v[188:191], v[0:3]
	s_add_i32 s63, s63, 2
	s_add_u32 s5, s5, 0x100
	s_addc_u32 s62, s62, 0
	s_cmp_gt_u32 s63, 29
	s_mov_b64 s[16:17], s[18:19]
	s_barrier
	s_cbranch_scc0 .LBB0_1077
	s_lshl_b32 s5, s60, 8
	s_add_i32 s12, s5, 0xfffff000
	s_ashr_i32 s12, s12, 11
	s_add_i32 s12, s12, 1
	s_cmp_lt_i32 s60, 16
	s_cselect_b32 s12, 0, s12
	v_add_u32_e32 v154, s5, v156
	v_lshl_or_b32 v152, s61, 8, v158
	s_mul_hi_i32 s15, s12, 0xc000
	s_mul_i32 s14, s12, 0xc000
	v_readlane_b32 s12, v254, 59
	v_readlane_b32 s13, v254, 63
	v_ashrrev_i32_e32 v155, 31, v154
	s_cselect_b32 s13, s12, s13
	v_readlane_b32 s12, v254, 61
	v_readlane_b32 s16, v255, 1
	v_ashrrev_i32_e32 v153, 31, v152
	v_lshlrev_b64 v[150:151], 11, v[154:155]
	s_cselect_b32 s12, s12, s16
	s_add_u32 s14, s35, s14
	v_lshl_add_u64 v[150:151], v[150:151], 0, v[152:153]
	s_addc_u32 s15, s39, s15
	v_lshlrev_b64 v[150:151], 2, v[150:151]
	v_lshl_add_u64 v[128:129], v[152:153], 2, s[14:15]
	v_lshl_add_u64 v[166:167], s[12:13], 0, v[150:151]
	global_load_dwordx4 v[140:143], v[128:129], off
	global_load_dwordx4 v[136:139], v[128:129], off offset:64
	global_load_dwordx4 v[132:135], v[128:129], off offset:512
	s_nop 0
	global_load_dwordx4 v[128:131], v[128:129], off offset:576
	v_readlane_b32 s68, v252, 37
	v_readlane_b32 s82, v252, 51
	v_readlane_b32 s83, v252, 52
	s_and_b64 vcc, exec, s[10:11]
	s_mov_b32 s61, s59
	s_mov_b32 s60, s4
	s_mov_b64 s[18:19], s[6:7]
	s_mov_b64 s[16:17], s[8:9]
	v_readlane_b32 s69, v252, 38
	v_readlane_b32 s70, v252, 39
	v_readlane_b32 s71, v252, 40
	v_readlane_b32 s72, v252, 41
	v_readlane_b32 s73, v252, 42
	v_readlane_b32 s74, v252, 43
	v_readlane_b32 s75, v252, 44
	v_readlane_b32 s76, v252, 45
	v_readlane_b32 s77, v252, 46
	v_readlane_b32 s78, v252, 47
	v_readlane_b32 s79, v252, 48
	v_readlane_b32 s80, v252, 49
	v_readlane_b32 s81, v252, 50
	s_nop 4
	v_mov_b32_e32 v145, v150
	v_add_u32_e32 v164, 0x20000, v145
	v_add_u32_e32 v165, 0x40000, v145
	v_add_u32_e32 v176, 0x60000, v145
	v_add_u32_e32 v177, 0x100000, v145
	v_add_u32_e32 v223, 0x120000, v145
	v_add_u32_e32 v248, 0x140000, v145
	v_add_u32_e32 v249, 0x160000, v145
	global_load_dwordx4 v[160:163], v145, s[12:13]
	global_load_dwordx4 v[168:171], v145, s[12:13] offset:64
	global_load_dwordx4 v[172:175], v145, s[12:13] offset:512
	global_load_dwordx4 v[180:183], v145, s[12:13] offset:576
	global_load_dwordx4 v[184:187], v164, s[12:13]
	global_load_dwordx4 v[188:191], v164, s[12:13] offset:64
	global_load_dwordx4 v[192:195], v164, s[12:13] offset:512
	global_load_dwordx4 v[196:199], v164, s[12:13] offset:576
	global_load_dwordx4 v[204:207], v165, s[12:13]
	global_load_dwordx4 v[212:215], v165, s[12:13] offset:64
	global_load_dwordx4 v[224:227], v165, s[12:13] offset:512
	global_load_dwordx4 v[228:231], v165, s[12:13] offset:576
	global_load_dwordx4 v[232:235], v176, s[12:13]
	global_load_dwordx4 v[236:239], v176, s[12:13] offset:64
	global_load_dwordx4 v[240:243], v176, s[12:13] offset:512
	global_load_dwordx4 v[244:247], v176, s[12:13] offset:576
	s_waitcnt vmcnt(15)
	v_pk_fma_f32 v[126:127], v[126:127], v[142:143], v[162:163]
	v_pk_fma_f32 v[124:125], v[124:125], v[140:141], v[160:161]
	global_store_dwordx4 v145, v[124:127], s[82:83]
	global_load_dwordx4 v[160:163], v177, s[12:13]
	s_waitcnt vmcnt(16)
	v_pk_fma_f32 v[122:123], v[122:123], v[138:139], v[170:171]
	v_pk_fma_f32 v[120:121], v[120:121], v[136:137], v[168:169]
	global_store_dwordx4 v145, v[120:123], s[82:83] offset:64
	global_load_dwordx4 v[168:171], v177, s[12:13] offset:64
	s_waitcnt vmcnt(17)
	v_pk_fma_f32 v[118:119], v[118:119], v[134:135], v[174:175]
	v_pk_fma_f32 v[116:117], v[116:117], v[132:133], v[172:173]
	global_store_dwordx4 v145, v[116:119], s[82:83] offset:512
	global_load_dwordx4 v[172:175], v177, s[12:13] offset:512
	s_waitcnt vmcnt(18)
	v_pk_fma_f32 v[114:115], v[114:115], v[130:131], v[182:183]
	v_pk_fma_f32 v[112:113], v[112:113], v[128:129], v[180:181]
	global_store_dwordx4 v145, v[112:115], s[82:83] offset:576
	global_load_dwordx4 v[180:183], v177, s[12:13] offset:576
	s_waitcnt vmcnt(19)
	v_pk_fma_f32 v[110:111], v[110:111], v[142:143], v[186:187]
	v_pk_fma_f32 v[108:109], v[108:109], v[140:141], v[184:185]
	global_store_dwordx4 v164, v[108:111], s[82:83]
	global_load_dwordx4 v[184:187], v223, s[12:13]
	s_waitcnt vmcnt(20)
	v_pk_fma_f32 v[106:107], v[106:107], v[138:139], v[190:191]
	v_pk_fma_f32 v[104:105], v[104:105], v[136:137], v[188:189]
	global_store_dwordx4 v164, v[104:107], s[82:83] offset:64
	global_load_dwordx4 v[188:191], v223, s[12:13] offset:64
	s_waitcnt vmcnt(21)
	v_pk_fma_f32 v[102:103], v[102:103], v[134:135], v[194:195]
	v_pk_fma_f32 v[100:101], v[100:101], v[132:133], v[192:193]
	global_store_dwordx4 v164, v[100:103], s[82:83] offset:512
	global_load_dwordx4 v[192:195], v223, s[12:13] offset:512
	s_waitcnt vmcnt(22)
	v_pk_fma_f32 v[98:99], v[98:99], v[130:131], v[198:199]
	v_pk_fma_f32 v[96:97], v[96:97], v[128:129], v[196:197]
	global_store_dwordx4 v164, v[96:99], s[82:83] offset:576
	global_load_dwordx4 v[196:199], v223, s[12:13] offset:576
	s_waitcnt vmcnt(23)
	v_pk_fma_f32 v[94:95], v[94:95], v[142:143], v[206:207]
	v_pk_fma_f32 v[92:93], v[92:93], v[140:141], v[204:205]
	global_store_dwordx4 v165, v[92:95], s[82:83]
	global_load_dwordx4 v[204:207], v248, s[12:13]
	s_waitcnt vmcnt(24)
	v_pk_fma_f32 v[90:91], v[90:91], v[138:139], v[214:215]
	v_pk_fma_f32 v[88:89], v[88:89], v[136:137], v[212:213]
	global_store_dwordx4 v165, v[88:91], s[82:83] offset:64
	global_load_dwordx4 v[212:215], v248, s[12:13] offset:64
	s_waitcnt vmcnt(25)
	v_pk_fma_f32 v[86:87], v[86:87], v[134:135], v[226:227]
	v_pk_fma_f32 v[84:85], v[84:85], v[132:133], v[224:225]
	global_store_dwordx4 v165, v[84:87], s[82:83] offset:512
	global_load_dwordx4 v[224:227], v248, s[12:13] offset:512
	s_waitcnt vmcnt(26)
	v_pk_fma_f32 v[82:83], v[82:83], v[130:131], v[230:231]
	v_pk_fma_f32 v[80:81], v[80:81], v[128:129], v[228:229]
	global_store_dwordx4 v165, v[80:83], s[82:83] offset:576
	global_load_dwordx4 v[228:231], v248, s[12:13] offset:576
	s_waitcnt vmcnt(27)
	v_pk_fma_f32 v[78:79], v[78:79], v[142:143], v[234:235]
	v_pk_fma_f32 v[76:77], v[76:77], v[140:141], v[232:233]
	global_store_dwordx4 v176, v[76:79], s[82:83]
	global_load_dwordx4 v[232:235], v249, s[12:13]
	s_waitcnt vmcnt(28)
	v_pk_fma_f32 v[74:75], v[74:75], v[138:139], v[238:239]
	v_pk_fma_f32 v[72:73], v[72:73], v[136:137], v[236:237]
	global_store_dwordx4 v176, v[72:75], s[82:83] offset:64
	global_load_dwordx4 v[236:239], v249, s[12:13] offset:64
	s_waitcnt vmcnt(29)
	v_pk_fma_f32 v[70:71], v[70:71], v[134:135], v[242:243]
	v_pk_fma_f32 v[68:69], v[68:69], v[132:133], v[240:241]
	global_store_dwordx4 v176, v[68:71], s[82:83] offset:512
	global_load_dwordx4 v[240:243], v249, s[12:13] offset:512
	s_waitcnt vmcnt(30)
	v_pk_fma_f32 v[66:67], v[66:67], v[130:131], v[246:247]
	v_pk_fma_f32 v[64:65], v[64:65], v[128:129], v[244:245]
	global_store_dwordx4 v176, v[64:67], s[82:83] offset:576
	global_load_dwordx4 v[244:247], v249, s[12:13] offset:576
	s_waitcnt vmcnt(30)
	v_pk_fma_f32 v[62:63], v[62:63], v[142:143], v[162:163]
	v_pk_fma_f32 v[60:61], v[60:61], v[140:141], v[160:161]
	global_store_dwordx4 v177, v[60:63], s[82:83]
	s_waitcnt vmcnt(29)
	v_pk_fma_f32 v[58:59], v[58:59], v[138:139], v[170:171]
	v_pk_fma_f32 v[56:57], v[56:57], v[136:137], v[168:169]
	global_store_dwordx4 v177, v[56:59], s[82:83] offset:64
	s_waitcnt vmcnt(28)
	v_pk_fma_f32 v[54:55], v[54:55], v[134:135], v[174:175]
	v_pk_fma_f32 v[52:53], v[52:53], v[132:133], v[172:173]
	global_store_dwordx4 v177, v[52:55], s[82:83] offset:512
	s_waitcnt vmcnt(27)
	v_pk_fma_f32 v[50:51], v[50:51], v[130:131], v[182:183]
	v_pk_fma_f32 v[48:49], v[48:49], v[128:129], v[180:181]
	global_store_dwordx4 v177, v[48:51], s[82:83] offset:576
	s_waitcnt vmcnt(26)
	v_pk_fma_f32 v[46:47], v[46:47], v[142:143], v[186:187]
	v_pk_fma_f32 v[44:45], v[44:45], v[140:141], v[184:185]
	global_store_dwordx4 v223, v[44:47], s[82:83]
	s_waitcnt vmcnt(25)
	v_pk_fma_f32 v[42:43], v[42:43], v[138:139], v[190:191]
	v_pk_fma_f32 v[40:41], v[40:41], v[136:137], v[188:189]
	global_store_dwordx4 v223, v[40:43], s[82:83] offset:64
	s_waitcnt vmcnt(24)
	v_pk_fma_f32 v[38:39], v[38:39], v[134:135], v[194:195]
	v_pk_fma_f32 v[36:37], v[36:37], v[132:133], v[192:193]
	global_store_dwordx4 v223, v[36:39], s[82:83] offset:512
	s_waitcnt vmcnt(23)
	v_pk_fma_f32 v[34:35], v[34:35], v[130:131], v[198:199]
	v_pk_fma_f32 v[32:33], v[32:33], v[128:129], v[196:197]
	global_store_dwordx4 v223, v[32:35], s[82:83] offset:576
	s_waitcnt vmcnt(22)
	v_pk_fma_f32 v[30:31], v[30:31], v[142:143], v[206:207]
	v_pk_fma_f32 v[28:29], v[28:29], v[140:141], v[204:205]
	global_store_dwordx4 v248, v[28:31], s[82:83]
	s_waitcnt vmcnt(21)
	v_pk_fma_f32 v[26:27], v[26:27], v[138:139], v[214:215]
	v_pk_fma_f32 v[24:25], v[24:25], v[136:137], v[212:213]
	global_store_dwordx4 v248, v[24:27], s[82:83] offset:64
	s_waitcnt vmcnt(20)
	v_pk_fma_f32 v[22:23], v[22:23], v[134:135], v[226:227]
	v_pk_fma_f32 v[20:21], v[20:21], v[132:133], v[224:225]
	global_store_dwordx4 v248, v[20:23], s[82:83] offset:512
	s_waitcnt vmcnt(19)
	v_pk_fma_f32 v[18:19], v[18:19], v[130:131], v[230:231]
	v_pk_fma_f32 v[16:17], v[16:17], v[128:129], v[228:229]
	global_store_dwordx4 v248, v[16:19], s[82:83] offset:576
	s_waitcnt vmcnt(18)
	v_pk_fma_f32 v[14:15], v[14:15], v[142:143], v[234:235]
	v_pk_fma_f32 v[12:13], v[12:13], v[140:141], v[232:233]
	global_store_dwordx4 v249, v[12:15], s[82:83]
	s_waitcnt vmcnt(17)
	v_pk_fma_f32 v[10:11], v[10:11], v[138:139], v[238:239]
	v_pk_fma_f32 v[8:9], v[8:9], v[136:137], v[236:237]
	global_store_dwordx4 v249, v[8:11], s[82:83] offset:64
	s_waitcnt vmcnt(16)
	v_pk_fma_f32 v[6:7], v[6:7], v[134:135], v[242:243]
	v_pk_fma_f32 v[4:5], v[4:5], v[132:133], v[240:241]
	global_store_dwordx4 v249, v[4:7], s[82:83] offset:512
	s_waitcnt vmcnt(15)
	v_pk_fma_f32 v[2:3], v[2:3], v[130:131], v[246:247]
	v_pk_fma_f32 v[0:1], v[0:1], v[128:129], v[244:245]
	global_store_dwordx4 v249, v[0:3], s[82:83] offset:576
	s_mov_b64 s[14:15], 0x160000
	s_cbranch_vccz .LBB0_1074
	s_waitcnt vmcnt(0)
	s_mov_b32 s4, s86
	s_cmp_gt_u32 s4, 3
	s_mov_b32 s34, 0x10000
	s_movk_i32 s57, 0x404
	s_cbranch_scc1 .LBB0_1081
	s_barrier

.LBB0_1198:
	s_add_u32 s70, s8, 0xfff80080
	s_addc_u32 s71, s9, -1
	s_add_i32 s77, 0, 0x10000
	v_add_u32_e32 v140, s77, v225
	ds_read_b128 v[128:131], v140
	ds_read_b128 v[132:135], v140 offset:1024
	ds_read_b128 v[136:139], v140 offset:2048
	ds_read_b128 v[140:143], v140 offset:3072
	s_cmp_eq_u32 s76, 28
	s_cselect_b32 s73, s5, s71
	s_cselect_b32 s72, s4, s70
	s_cselect_b32 s71, s7, s75
	s_cselect_b32 s70, s6, s35
	s_add_i32 m0, s84, 0xc000
	ds_read_b128 v[144:147], v226
	ds_read_b128 v[148:151], v226 offset:1024
	ds_read_b128 v[152:155], v226 offset:2048
	ds_read_b128 v[156:159], v226 offset:3072
	ds_read_b128 v[160:163], v226 offset:4096
	ds_read_b128 v[164:167], v226 offset:5120
	ds_read_b128 v[168:171], v226 offset:6144
	ds_read_b128 v[172:175], v226 offset:7168
	global_load_lds_dwordx4 v190, s[8:9]
	s_add_i32 m0, s84, 0xe000
	s_nop 0
	global_load_lds_dwordx4 v188, s[8:9]
	s_waitcnt lgkmcnt(8)
	s_barrier
	s_waitcnt lgkmcnt(0)
	v_mfma_f32_16x16x32_bf16 v[124:127], v[128:131], v[144:147], v[124:127]
	v_mfma_f32_16x16x32_bf16 v[60:63], v[136:139], v[144:147], v[60:63]
	v_mfma_f32_16x16x32_bf16 v[116:119], v[128:131], v[152:155], v[116:119]
	v_mfma_f32_16x16x32_bf16 v[52:55], v[136:139], v[152:155], v[52:55]
	v_mfma_f32_16x16x32_bf16 v[108:111], v[128:131], v[160:163], v[108:111]
	v_mfma_f32_16x16x32_bf16 v[44:47], v[136:139], v[160:163], v[44:47]
	v_mfma_f32_16x16x32_bf16 v[100:103], v[128:131], v[168:171], v[100:103]
	v_mfma_f32_16x16x32_bf16 v[36:39], v[136:139], v[168:171], v[36:39]
	v_mfma_f32_16x16x32_bf16 v[124:127], v[132:135], v[148:151], v[124:127]
	v_mfma_f32_16x16x32_bf16 v[60:63], v[140:143], v[148:151], v[60:63]
	v_mfma_f32_16x16x32_bf16 v[116:119], v[132:135], v[156:159], v[116:119]
	v_mfma_f32_16x16x32_bf16 v[52:55], v[140:143], v[156:159], v[52:55]
	v_mfma_f32_16x16x32_bf16 v[108:111], v[132:135], v[164:167], v[108:111]
	v_mfma_f32_16x16x32_bf16 v[44:47], v[140:143], v[164:167], v[44:47]
	v_mfma_f32_16x16x32_bf16 v[100:103], v[132:135], v[172:175], v[100:103]
	v_mfma_f32_16x16x32_bf16 v[36:39], v[140:143], v[172:175], v[36:39]
	s_barrier
	s_add_i32 vcc_lo, 0, 0x14000
	v_add_u32_e32 v176, vcc_lo, v225
	s_add_i32 s77, s77, s24
	ds_read_b128 v[192:195], v176
	ds_read_b128 v[196:199], v176 offset:1024
	ds_read_b128 v[204:207], v176 offset:2048
	ds_read_b128 v[212:215], v176 offset:3072
	s_mov_b32 m0, s77
	global_load_lds_dwordx4 v182, s[70:71]
	s_add_i32 m0, s77, 0x2000
	s_nop 0
	global_load_lds_dwordx4 v186, s[70:71]
	s_barrier
	s_waitcnt lgkmcnt(0)
	v_mfma_f32_16x16x32_bf16 v[120:123], v[192:195], v[144:147], v[120:123]
	v_mfma_f32_16x16x32_bf16 v[56:59], v[204:207], v[144:147], v[56:59]
	v_mfma_f32_16x16x32_bf16 v[112:115], v[192:195], v[152:155], v[112:115]
	v_mfma_f32_16x16x32_bf16 v[48:51], v[204:207], v[152:155], v[48:51]
	v_mfma_f32_16x16x32_bf16 v[104:107], v[192:195], v[160:163], v[104:107]
	v_mfma_f32_16x16x32_bf16 v[40:43], v[204:207], v[160:163], v[40:43]
	v_mfma_f32_16x16x32_bf16 v[96:99], v[192:195], v[168:171], v[96:99]
	v_mfma_f32_16x16x32_bf16 v[32:35], v[204:207], v[168:171], v[32:35]
	v_mfma_f32_16x16x32_bf16 v[120:123], v[196:199], v[148:151], v[120:123]
	v_mfma_f32_16x16x32_bf16 v[56:59], v[212:215], v[148:151], v[56:59]
	v_mfma_f32_16x16x32_bf16 v[112:115], v[196:199], v[156:159], v[112:115]
	v_mfma_f32_16x16x32_bf16 v[48:51], v[212:215], v[156:159], v[48:51]
	v_mfma_f32_16x16x32_bf16 v[104:107], v[196:199], v[164:167], v[104:107]
	v_mfma_f32_16x16x32_bf16 v[40:43], v[212:215], v[164:167], v[40:43]
	v_mfma_f32_16x16x32_bf16 v[96:99], v[196:199], v[172:175], v[96:99]
	v_mfma_f32_16x16x32_bf16 v[32:35], v[212:215], v[172:175], v[32:35]
	s_mov_b32 m0, s84
	s_mov_b64 s[100:101], s[72:73]
	s_barrier
	ds_read_b128 v[144:147], v226 offset:16384
	ds_read_b128 v[148:151], v226 offset:17408
	ds_read_b128 v[152:155], v226 offset:18432
	ds_read_b128 v[156:159], v226 offset:19456
	ds_read_b128 v[160:163], v226 offset:20480
	ds_read_b128 v[164:167], v226 offset:21504
	ds_read_b128 v[168:171], v226 offset:22528
	ds_read_b128 v[172:175], v226 offset:23552
	global_load_lds_dwordx4 v180, s[72:73]
	s_mov_b64 s[100:101], s[72:73]
	s_mov_b32 m0, s85
	s_nop 0
	global_load_lds_dwordx4 v184, s[72:73]
	s_barrier
	s_waitcnt lgkmcnt(0)
	v_mfma_f32_16x16x32_bf16 v[92:95], v[128:131], v[144:147], v[92:95]
	v_mfma_f32_16x16x32_bf16 v[28:31], v[136:139], v[144:147], v[28:31]
	v_mfma_f32_16x16x32_bf16 v[84:87], v[128:131], v[152:155], v[84:87]
	v_mfma_f32_16x16x32_bf16 v[20:23], v[136:139], v[152:155], v[20:23]
	v_mfma_f32_16x16x32_bf16 v[76:79], v[128:131], v[160:163], v[76:79]
	v_mfma_f32_16x16x32_bf16 v[12:15], v[136:139], v[160:163], v[12:15]
	v_mfma_f32_16x16x32_bf16 v[68:71], v[128:131], v[168:171], v[68:71]
	v_mfma_f32_16x16x32_bf16 v[4:7], v[136:139], v[168:171], v[4:7]
	v_mfma_f32_16x16x32_bf16 v[92:95], v[132:135], v[148:151], v[92:95]
	v_mfma_f32_16x16x32_bf16 v[28:31], v[140:143], v[148:151], v[28:31]
	v_mfma_f32_16x16x32_bf16 v[84:87], v[132:135], v[156:159], v[84:87]
	v_mfma_f32_16x16x32_bf16 v[20:23], v[140:143], v[156:159], v[20:23]
	v_mfma_f32_16x16x32_bf16 v[76:79], v[132:135], v[164:167], v[76:79]
	v_mfma_f32_16x16x32_bf16 v[12:15], v[140:143], v[164:167], v[12:15]
	v_mfma_f32_16x16x32_bf16 v[68:71], v[132:135], v[172:175], v[68:71]
	v_mfma_f32_16x16x32_bf16 v[4:7], v[140:143], v[172:175], v[4:7]
	s_barrier
	s_add_u32 s78, s70, 0x80000
	s_addc_u32 s79, s71, 0
	s_add_i32 s77, vcc_lo, s24
	s_mov_b32 m0, s77
	s_nop 0
	global_load_lds_dwordx4 v182, s[78:79]
	s_add_i32 m0, s77, 0x2000
	s_nop 0
	global_load_lds_dwordx4 v186, s[78:79]
	s_waitcnt vmcnt(6)
	s_barrier
	v_mfma_f32_16x16x32_bf16 v[88:91], v[192:195], v[144:147], v[88:91]
	v_mfma_f32_16x16x32_bf16 v[24:27], v[204:207], v[144:147], v[24:27]
	v_mfma_f32_16x16x32_bf16 v[80:83], v[192:195], v[152:155], v[80:83]
	v_mfma_f32_16x16x32_bf16 v[16:19], v[204:207], v[152:155], v[16:19]
	v_mfma_f32_16x16x32_bf16 v[72:75], v[192:195], v[160:163], v[72:75]
	v_mfma_f32_16x16x32_bf16 v[8:11], v[204:207], v[160:163], v[8:11]
	v_mfma_f32_16x16x32_bf16 v[64:67], v[192:195], v[168:171], v[64:67]
	v_mfma_f32_16x16x32_bf16 v[0:3], v[204:207], v[168:171], v[0:3]
	v_mfma_f32_16x16x32_bf16 v[88:91], v[196:199], v[148:151], v[88:91]
	v_mfma_f32_16x16x32_bf16 v[24:27], v[212:215], v[148:151], v[24:27]
	v_mfma_f32_16x16x32_bf16 v[80:83], v[196:199], v[156:159], v[80:83]
	v_mfma_f32_16x16x32_bf16 v[16:19], v[212:215], v[156:159], v[16:19]
	v_mfma_f32_16x16x32_bf16 v[72:75], v[196:199], v[164:167], v[72:75]
	v_mfma_f32_16x16x32_bf16 v[8:11], v[212:215], v[164:167], v[8:11]
	v_mfma_f32_16x16x32_bf16 v[64:67], v[196:199], v[172:175], v[64:67]
	v_mfma_f32_16x16x32_bf16 v[0:3], v[212:215], v[172:175], v[0:3]
	s_add_i32 s77, 0, 0x18000
	v_add_u32_e32 v140, s77, v225
	s_barrier
	ds_read_b128 v[128:131], v140
	ds_read_b128 v[132:135], v140 offset:1024
	ds_read_b128 v[136:139], v140 offset:2048
	ds_read_b128 v[140:143], v140 offset:3072
	s_add_u32 s72, s72, 0x80000
	s_addc_u32 s73, s73, 0
	s_mov_b32 m0, s86
	ds_read_b128 v[144:147], v226 offset:32768
	ds_read_b128 v[148:151], v226 offset:33792
	ds_read_b128 v[152:155], v226 offset:34816
	ds_read_b128 v[156:159], v226 offset:35840
	ds_read_b128 v[160:163], v226 offset:36864
	ds_read_b128 v[164:167], v226 offset:37888
	ds_read_b128 v[168:171], v226 offset:38912
	ds_read_b128 v[172:175], v226 offset:39936
	global_load_lds_dwordx4 v180, s[72:73]
	s_mov_b32 m0, s87
	s_nop 0
	global_load_lds_dwordx4 v184, s[72:73]
	s_waitcnt lgkmcnt(8)
	s_barrier
	s_waitcnt lgkmcnt(0)
	v_mfma_f32_16x16x32_bf16 v[124:127], v[128:131], v[144:147], v[124:127]
	v_mfma_f32_16x16x32_bf16 v[60:63], v[136:139], v[144:147], v[60:63]
	v_mfma_f32_16x16x32_bf16 v[116:119], v[128:131], v[152:155], v[116:119]
	v_mfma_f32_16x16x32_bf16 v[52:55], v[136:139], v[152:155], v[52:55]
	v_mfma_f32_16x16x32_bf16 v[108:111], v[128:131], v[160:163], v[108:111]
	v_mfma_f32_16x16x32_bf16 v[44:47], v[136:139], v[160:163], v[44:47]
	v_mfma_f32_16x16x32_bf16 v[100:103], v[128:131], v[168:171], v[100:103]
	v_mfma_f32_16x16x32_bf16 v[36:39], v[136:139], v[168:171], v[36:39]
	v_mfma_f32_16x16x32_bf16 v[124:127], v[132:135], v[148:151], v[124:127]
	v_mfma_f32_16x16x32_bf16 v[60:63], v[140:143], v[148:151], v[60:63]
	v_mfma_f32_16x16x32_bf16 v[116:119], v[132:135], v[156:159], v[116:119]
	v_mfma_f32_16x16x32_bf16 v[52:55], v[140:143], v[156:159], v[52:55]
	v_mfma_f32_16x16x32_bf16 v[108:111], v[132:135], v[164:167], v[108:111]
	v_mfma_f32_16x16x32_bf16 v[44:47], v[140:143], v[164:167], v[44:47]
	v_mfma_f32_16x16x32_bf16 v[100:103], v[132:135], v[172:175], v[100:103]
	v_mfma_f32_16x16x32_bf16 v[36:39], v[140:143], v[172:175], v[36:39]
	s_barrier
	s_add_i32 s72, 0, 0x1c000
	s_add_i32 s73, s77, s24
	v_add_u32_e32 v178, s72, v225
	s_add_i32 m0, s73, 0xffffff80
	ds_read_b128 v[192:195], v178
	ds_read_b128 v[196:199], v178 offset:1024
	ds_read_b128 v[204:207], v178 offset:2048
	ds_read_b128 v[212:215], v178 offset:3072
	global_load_lds_dwordx4 v182, s[70:71] offset:128
	s_add_i32 m0, s73, 0x1f80
	s_nop 0
	global_load_lds_dwordx4 v186, s[70:71] offset:128
	s_barrier
	s_waitcnt lgkmcnt(0)
	v_mfma_f32_16x16x32_bf16 v[120:123], v[192:195], v[144:147], v[120:123]
	v_mfma_f32_16x16x32_bf16 v[56:59], v[204:207], v[144:147], v[56:59]
	v_mfma_f32_16x16x32_bf16 v[112:115], v[192:195], v[152:155], v[112:115]
	v_mfma_f32_16x16x32_bf16 v[48:51], v[204:207], v[152:155], v[48:51]
	v_mfma_f32_16x16x32_bf16 v[104:107], v[192:195], v[160:163], v[104:107]
	v_mfma_f32_16x16x32_bf16 v[40:43], v[204:207], v[160:163], v[40:43]
	v_mfma_f32_16x16x32_bf16 v[96:99], v[192:195], v[168:171], v[96:99]
	v_mfma_f32_16x16x32_bf16 v[32:35], v[204:207], v[168:171], v[32:35]
	v_mfma_f32_16x16x32_bf16 v[120:123], v[196:199], v[148:151], v[120:123]
	v_mfma_f32_16x16x32_bf16 v[56:59], v[212:215], v[148:151], v[56:59]
	v_mfma_f32_16x16x32_bf16 v[112:115], v[196:199], v[156:159], v[112:115]
	v_mfma_f32_16x16x32_bf16 v[48:51], v[212:215], v[156:159], v[48:51]
	v_mfma_f32_16x16x32_bf16 v[104:107], v[196:199], v[164:167], v[104:107]
	v_mfma_f32_16x16x32_bf16 v[40:43], v[212:215], v[164:167], v[40:43]
	v_mfma_f32_16x16x32_bf16 v[96:99], v[196:199], v[172:175], v[96:99]
	v_mfma_f32_16x16x32_bf16 v[32:35], v[212:215], v[172:175], v[32:35]
	s_add_i32 m0, s59, 0xffffff80
	s_barrier
	ds_read_b128 v[144:147], v226 offset:49152
	ds_read_b128 v[148:151], v226 offset:50176
	ds_read_b128 v[152:155], v226 offset:51200
	ds_read_b128 v[156:159], v226 offset:52224
	ds_read_b128 v[160:163], v226 offset:53248
	ds_read_b128 v[164:167], v226 offset:54272
	ds_read_b128 v[168:171], v226 offset:55296
	ds_read_b128 v[172:175], v226 offset:56320
	global_load_lds_dwordx4 v180, s[100:101] offset:128
	s_add_i32 m0, s20, 0xffffff80
	s_nop 0
	global_load_lds_dwordx4 v184, s[100:101] offset:128
	s_barrier
	s_waitcnt lgkmcnt(0)
	v_mfma_f32_16x16x32_bf16 v[92:95], v[128:131], v[144:147], v[92:95]
	v_mfma_f32_16x16x32_bf16 v[28:31], v[136:139], v[144:147], v[28:31]
	v_mfma_f32_16x16x32_bf16 v[84:87], v[128:131], v[152:155], v[84:87]
	v_mfma_f32_16x16x32_bf16 v[20:23], v[136:139], v[152:155], v[20:23]
	v_mfma_f32_16x16x32_bf16 v[76:79], v[128:131], v[160:163], v[76:79]
	v_mfma_f32_16x16x32_bf16 v[12:15], v[136:139], v[160:163], v[12:15]
	v_mfma_f32_16x16x32_bf16 v[68:71], v[128:131], v[168:171], v[68:71]
	v_mfma_f32_16x16x32_bf16 v[4:7], v[136:139], v[168:171], v[4:7]
	v_mfma_f32_16x16x32_bf16 v[92:95], v[132:135], v[148:151], v[92:95]
	v_mfma_f32_16x16x32_bf16 v[28:31], v[140:143], v[148:151], v[28:31]
	v_mfma_f32_16x16x32_bf16 v[84:87], v[132:135], v[156:159], v[84:87]
	v_mfma_f32_16x16x32_bf16 v[20:23], v[140:143], v[156:159], v[20:23]
	v_mfma_f32_16x16x32_bf16 v[76:79], v[132:135], v[164:167], v[76:79]
	v_mfma_f32_16x16x32_bf16 v[12:15], v[140:143], v[164:167], v[12:15]
	v_mfma_f32_16x16x32_bf16 v[68:71], v[132:135], v[172:175], v[68:71]
	v_mfma_f32_16x16x32_bf16 v[4:7], v[140:143], v[172:175], v[4:7]
	s_barrier
	s_add_u32 s70, s70, 0x80080
	s_addc_u32 s71, s71, 0
	s_add_i32 s72, s72, s24
	s_mov_b32 m0, s72
	s_nop 0
	global_load_lds_dwordx4 v182, s[70:71]
	s_add_i32 m0, s72, 0x2000
	s_nop 0
	global_load_lds_dwordx4 v186, s[70:71]
	s_waitcnt vmcnt(6)
	s_barrier
	v_mfma_f32_16x16x32_bf16 v[88:91], v[192:195], v[144:147], v[88:91]
	v_mfma_f32_16x16x32_bf16 v[24:27], v[204:207], v[144:147], v[24:27]
	v_mfma_f32_16x16x32_bf16 v[80:83], v[192:195], v[152:155], v[80:83]
	v_mfma_f32_16x16x32_bf16 v[16:19], v[204:207], v[152:155], v[16:19]
	v_mfma_f32_16x16x32_bf16 v[72:75], v[192:195], v[160:163], v[72:75]
	v_mfma_f32_16x16x32_bf16 v[8:11], v[204:207], v[160:163], v[8:11]
	v_mfma_f32_16x16x32_bf16 v[64:67], v[192:195], v[168:171], v[64:67]
	v_mfma_f32_16x16x32_bf16 v[0:3], v[204:207], v[168:171], v[0:3]
	v_mfma_f32_16x16x32_bf16 v[88:91], v[196:199], v[148:151], v[88:91]
	v_mfma_f32_16x16x32_bf16 v[24:27], v[212:215], v[148:151], v[24:27]
	v_mfma_f32_16x16x32_bf16 v[80:83], v[196:199], v[156:159], v[80:83]
	v_mfma_f32_16x16x32_bf16 v[16:19], v[212:215], v[156:159], v[16:19]
	v_mfma_f32_16x16x32_bf16 v[72:75], v[196:199], v[164:167], v[72:75]
	v_mfma_f32_16x16x32_bf16 v[8:11], v[212:215], v[164:167], v[8:11]
	v_mfma_f32_16x16x32_bf16 v[64:67], v[196:199], v[172:175], v[64:67]
	v_mfma_f32_16x16x32_bf16 v[0:3], v[212:215], v[172:175], v[0:3]
	s_add_i32 s76, s76, 2
	s_add_u32 s35, s35, 0x100
	s_addc_u32 s75, s75, 0
	s_add_u32 s8, s8, 0x100
	s_addc_u32 s9, s9, 0
	s_cmp_gt_u32 s76, 29
	s_barrier
	s_cbranch_scc0 .LBB0_1198
	v_mov_b32_e32 v140, v224
	v_mov_b32_e32 v194, v223
	v_readlane_b32 s4, v255, 16
	v_lshlrev_b32_e32 v227, 6, v140
	v_cmp_lt_i32_e32 vcc, 14, v194
	v_add_u32_e32 v141, s4, v227
	s_mov_b64 s[4:5], 0
	s_and_saveexec_b64 s[6:7], vcc
	s_xor_b64 s[6:7], exec, s[6:7]
	s_cbranch_execz .LBB0_1203
	v_cmp_eq_u32_e32 vcc, 15, v194
	s_and_saveexec_b64 s[8:9], vcc
	s_mov_b64 s[4:5], exec
	ds_write_b128 v141, v[100:103] offset:256
	s_or_b64 exec, exec, s[8:9]
	s_and_b64 s[4:5], s[4:5], exec

.LBB0_1363:
	s_add_u32 s16, s14, 0x100
	s_addc_u32 s17, s15, 0
	s_add_i32 s68, 0, 0x10000
	v_add_u32_e32 v76, s68, v153
	ds_read_b128 v[48:51], v76
	ds_read_b128 v[68:71], v76 offset:1024
	ds_read_b128 v[72:75], v76 offset:2048
	ds_read_b128 v[76:79], v76 offset:3072
	s_cmpk_eq_i32 s67, 0x52
	s_cselect_b32 s21, s11, s17
	s_cselect_b32 s20, s10, s16
	s_cselect_b32 s19, s13, s66
	s_cselect_b32 s18, s12, s63
	v_lshl_add_u64 v[150:151], s[14:15], 0, v[148:149]
	s_add_i32 m0, s29, 0xc000
	ds_read_b128 v[156:159], v155
	ds_read_b128 v[160:163], v155 offset:1024
	ds_read_b128 v[164:167], v155 offset:2048
	ds_read_b128 v[168:171], v155 offset:3072
	ds_read_b128 v[172:175], v155 offset:4096
	ds_read_b128 v[180:183], v155 offset:5120
	ds_read_b128 v[184:187], v155 offset:6144
	ds_read_b128 v[188:191], v155 offset:7168
	global_load_lds_dwordx4 v[150:151], off
	v_lshl_add_u64 v[150:151], s[14:15], 0, v[146:147]
	s_add_i32 m0, s29, 0xe000
	s_nop 0
	global_load_lds_dwordx4 v[150:151], off
	s_waitcnt lgkmcnt(8)
	s_barrier
	s_waitcnt lgkmcnt(0)
	v_mfma_f32_16x16x32_bf16 v[140:143], v[48:51], v[156:159], v[140:143]
	v_mfma_f32_16x16x32_bf16 v[136:139], v[72:75], v[156:159], v[136:139]
	v_mfma_f32_16x16x32_bf16 v[124:127], v[48:51], v[164:167], v[124:127]
	v_mfma_f32_16x16x32_bf16 v[120:123], v[72:75], v[164:167], v[120:123]
	v_mfma_f32_16x16x32_bf16 v[116:119], v[48:51], v[172:175], v[116:119]
	v_mfma_f32_16x16x32_bf16 v[112:115], v[72:75], v[172:175], v[112:115]
	v_mfma_f32_16x16x32_bf16 v[100:103], v[48:51], v[184:187], v[100:103]
	v_mfma_f32_16x16x32_bf16 v[96:99], v[72:75], v[184:187], v[96:99]
	v_mfma_f32_16x16x32_bf16 v[140:143], v[68:71], v[160:163], v[140:143]
	v_mfma_f32_16x16x32_bf16 v[136:139], v[76:79], v[160:163], v[136:139]
	v_mfma_f32_16x16x32_bf16 v[124:127], v[68:71], v[168:171], v[124:127]
	v_mfma_f32_16x16x32_bf16 v[120:123], v[76:79], v[168:171], v[120:123]
	v_mfma_f32_16x16x32_bf16 v[116:119], v[68:71], v[180:183], v[116:119]
	v_mfma_f32_16x16x32_bf16 v[112:115], v[76:79], v[180:183], v[112:115]
	v_mfma_f32_16x16x32_bf16 v[100:103], v[68:71], v[188:191], v[100:103]
	v_mfma_f32_16x16x32_bf16 v[96:99], v[76:79], v[188:191], v[96:99]
	s_barrier
	s_add_i32 s69, 0, 0x14000
	v_add_u32_e32 v150, s69, v153
	s_add_i32 s14, s68, s28
	ds_read_b128 v[192:195], v150
	ds_read_b128 v[196:199], v150 offset:1024
	ds_read_b128 v[204:207], v150 offset:2048
	ds_read_b128 v[212:215], v150 offset:3072
	s_mov_b32 m0, s14
	global_load_lds_dwordx4 v178, s[18:19]
	s_add_i32 m0, s14, 0x2000
	s_nop 0
	global_load_lds_dwordx4 v144, s[18:19]
	s_barrier
	s_waitcnt lgkmcnt(0)
	v_mfma_f32_16x16x32_bf16 v[132:135], v[192:195], v[156:159], v[132:135]
	v_mfma_f32_16x16x32_bf16 v[128:131], v[204:207], v[156:159], v[128:131]
	v_mfma_f32_16x16x32_bf16 v[108:111], v[192:195], v[164:167], v[108:111]
	v_mfma_f32_16x16x32_bf16 v[104:107], v[204:207], v[164:167], v[104:107]
	v_mfma_f32_16x16x32_bf16 v[92:95], v[192:195], v[172:175], v[92:95]
	v_mfma_f32_16x16x32_bf16 v[88:91], v[204:207], v[172:175], v[88:91]
	v_mfma_f32_16x16x32_bf16 v[84:87], v[192:195], v[184:187], v[84:87]
	v_mfma_f32_16x16x32_bf16 v[80:83], v[204:207], v[184:187], v[80:83]
	v_mfma_f32_16x16x32_bf16 v[132:135], v[196:199], v[160:163], v[132:135]
	v_mfma_f32_16x16x32_bf16 v[128:131], v[212:215], v[160:163], v[128:131]
	v_mfma_f32_16x16x32_bf16 v[108:111], v[196:199], v[168:171], v[108:111]
	v_mfma_f32_16x16x32_bf16 v[104:107], v[212:215], v[168:171], v[104:107]
	v_mfma_f32_16x16x32_bf16 v[92:95], v[196:199], v[180:183], v[92:95]
	v_mfma_f32_16x16x32_bf16 v[88:91], v[212:215], v[180:183], v[88:91]
	v_mfma_f32_16x16x32_bf16 v[84:87], v[196:199], v[188:191], v[84:87]
	v_mfma_f32_16x16x32_bf16 v[80:83], v[212:215], v[188:191], v[80:83]
	s_mov_b32 m0, s29
	s_mov_b64 s[100:101], s[20:21]
	s_barrier
	ds_read_b128 v[156:159], v155 offset:16384
	ds_read_b128 v[160:163], v155 offset:17408
	ds_read_b128 v[164:167], v155 offset:18432
	ds_read_b128 v[168:171], v155 offset:19456
	ds_read_b128 v[172:175], v155 offset:20480
	ds_read_b128 v[180:183], v155 offset:21504
	ds_read_b128 v[184:187], v155 offset:22528
	ds_read_b128 v[188:191], v155 offset:23552
	global_load_lds_dwordx4 v178, s[20:21]
	s_mov_b64 s[100:101], s[20:21]
	s_mov_b32 m0, s30
	s_nop 0
	global_load_lds_dwordx4 v144, s[20:21]
	s_barrier
	s_waitcnt lgkmcnt(0)
	v_mfma_f32_16x16x32_bf16 v[64:67], v[48:51], v[156:159], v[64:67]
	v_mfma_f32_16x16x32_bf16 v[60:63], v[72:75], v[156:159], v[60:63]
	v_mfma_f32_16x16x32_bf16 v[44:47], v[48:51], v[164:167], v[44:47]
	v_mfma_f32_16x16x32_bf16 v[40:43], v[72:75], v[164:167], v[40:43]
	v_mfma_f32_16x16x32_bf16 v[28:31], v[48:51], v[172:175], v[28:31]
	v_mfma_f32_16x16x32_bf16 v[24:27], v[72:75], v[172:175], v[24:27]
	v_mfma_f32_16x16x32_bf16 v[12:15], v[48:51], v[184:187], v[12:15]
	v_mfma_f32_16x16x32_bf16 v[8:11], v[72:75], v[184:187], v[8:11]
	v_mfma_f32_16x16x32_bf16 v[64:67], v[68:71], v[160:163], v[64:67]
	v_mfma_f32_16x16x32_bf16 v[60:63], v[76:79], v[160:163], v[60:63]
	v_mfma_f32_16x16x32_bf16 v[44:47], v[68:71], v[168:171], v[44:47]
	v_mfma_f32_16x16x32_bf16 v[40:43], v[76:79], v[168:171], v[40:43]
	v_mfma_f32_16x16x32_bf16 v[28:31], v[68:71], v[180:183], v[28:31]
	v_mfma_f32_16x16x32_bf16 v[24:27], v[76:79], v[180:183], v[24:27]
	v_mfma_f32_16x16x32_bf16 v[12:15], v[68:71], v[188:191], v[12:15]
	v_mfma_f32_16x16x32_bf16 v[8:11], v[76:79], v[188:191], v[8:11]
	s_barrier
	s_add_u32 s14, s18, 0x158000
	s_addc_u32 s15, s19, 0
	s_add_i32 s68, s69, s28
	s_mov_b32 m0, s68
	s_nop 0
	global_load_lds_dwordx4 v178, s[14:15]
	s_add_i32 m0, s68, 0x2000
	s_nop 0
	global_load_lds_dwordx4 v144, s[14:15]
	s_waitcnt vmcnt(6)
	s_barrier
	v_mfma_f32_16x16x32_bf16 v[52:55], v[204:207], v[156:159], v[52:55]
	v_mfma_f32_16x16x32_bf16 v[36:39], v[192:195], v[164:167], v[36:39]
	v_mfma_f32_16x16x32_bf16 v[32:35], v[204:207], v[164:167], v[32:35]
	v_mfma_f32_16x16x32_bf16 v[20:23], v[192:195], v[172:175], v[20:23]
	v_mfma_f32_16x16x32_bf16 v[16:19], v[204:207], v[172:175], v[16:19]
	v_mfma_f32_16x16x32_bf16 v[4:7], v[192:195], v[184:187], v[4:7]
	v_mfma_f32_16x16x32_bf16 v[0:3], v[204:207], v[184:187], v[0:3]
	v_mfma_f32_16x16x32_bf16 v[48:51], v[192:195], v[156:159], v[56:59]
	v_mfma_f32_16x16x32_bf16 v[52:55], v[212:215], v[160:163], v[52:55]
	v_mfma_f32_16x16x32_bf16 v[36:39], v[196:199], v[168:171], v[36:39]
	v_mfma_f32_16x16x32_bf16 v[32:35], v[212:215], v[168:171], v[32:35]
	v_mfma_f32_16x16x32_bf16 v[20:23], v[196:199], v[180:183], v[20:23]
	v_mfma_f32_16x16x32_bf16 v[16:19], v[212:215], v[180:183], v[16:19]
	v_mfma_f32_16x16x32_bf16 v[4:7], v[196:199], v[188:191], v[4:7]
	v_mfma_f32_16x16x32_bf16 v[0:3], v[212:215], v[188:191], v[0:3]
	v_mfma_f32_16x16x32_bf16 v[48:51], v[196:199], v[160:163], v[48:51]
	s_add_i32 s68, 0, 0x18000
	v_add_u32_e32 v76, s68, v153
	s_barrier
	ds_read_b128 v[56:59], v76
	ds_read_b128 v[68:71], v76 offset:1024
	ds_read_b128 v[72:75], v76 offset:2048
	ds_read_b128 v[76:79], v76 offset:3072
	s_add_u32 s14, s20, 0x158000
	s_addc_u32 s15, s21, 0
	s_mov_b32 m0, s31
	ds_read_b128 v[156:159], v155 offset:32768
	ds_read_b128 v[160:163], v155 offset:33792
	ds_read_b128 v[164:167], v155 offset:34816
	ds_read_b128 v[168:171], v155 offset:35840
	ds_read_b128 v[172:175], v155 offset:36864
	ds_read_b128 v[180:183], v155 offset:37888
	ds_read_b128 v[184:187], v155 offset:38912
	ds_read_b128 v[188:191], v155 offset:39936
	global_load_lds_dwordx4 v178, s[14:15]
	s_mov_b32 m0, s34
	s_nop 0
	global_load_lds_dwordx4 v144, s[14:15]
	s_waitcnt lgkmcnt(8)
	s_barrier
	s_waitcnt lgkmcnt(0)
	v_mfma_f32_16x16x32_bf16 v[140:143], v[56:59], v[156:159], v[140:143]
	v_mfma_f32_16x16x32_bf16 v[136:139], v[72:75], v[156:159], v[136:139]
	v_mfma_f32_16x16x32_bf16 v[124:127], v[56:59], v[164:167], v[124:127]
	v_mfma_f32_16x16x32_bf16 v[120:123], v[72:75], v[164:167], v[120:123]
	v_mfma_f32_16x16x32_bf16 v[116:119], v[56:59], v[172:175], v[116:119]
	v_mfma_f32_16x16x32_bf16 v[112:115], v[72:75], v[172:175], v[112:115]
	v_mfma_f32_16x16x32_bf16 v[100:103], v[56:59], v[184:187], v[100:103]
	v_mfma_f32_16x16x32_bf16 v[96:99], v[72:75], v[184:187], v[96:99]
	v_mfma_f32_16x16x32_bf16 v[140:143], v[68:71], v[160:163], v[140:143]
	v_mfma_f32_16x16x32_bf16 v[136:139], v[76:79], v[160:163], v[136:139]
	v_mfma_f32_16x16x32_bf16 v[124:127], v[68:71], v[168:171], v[124:127]
	v_mfma_f32_16x16x32_bf16 v[120:123], v[76:79], v[168:171], v[120:123]
	v_mfma_f32_16x16x32_bf16 v[116:119], v[68:71], v[180:183], v[116:119]
	v_mfma_f32_16x16x32_bf16 v[112:115], v[76:79], v[180:183], v[112:115]
	v_mfma_f32_16x16x32_bf16 v[100:103], v[68:71], v[188:191], v[100:103]
	v_mfma_f32_16x16x32_bf16 v[96:99], v[76:79], v[188:191], v[96:99]
	s_barrier
	s_add_i32 s20, 0, 0x1c000
	s_add_i32 s14, s68, s28
	v_add_u32_e32 v212, s20, v153
	s_add_i32 m0, s14, 0xffffff80
	ds_read_b128 v[192:195], v212
	ds_read_b128 v[196:199], v212 offset:1024
	ds_read_b128 v[204:207], v212 offset:2048
	ds_read_b128 v[212:215], v212 offset:3072
	global_load_lds_dwordx4 v178, s[18:19] offset:128
	s_add_i32 m0, s14, 0x1f80
	s_nop 0
	global_load_lds_dwordx4 v144, s[18:19] offset:128
	s_barrier
	s_waitcnt lgkmcnt(0)
	v_mfma_f32_16x16x32_bf16 v[132:135], v[192:195], v[156:159], v[132:135]
	v_mfma_f32_16x16x32_bf16 v[128:131], v[204:207], v[156:159], v[128:131]
	v_mfma_f32_16x16x32_bf16 v[108:111], v[192:195], v[164:167], v[108:111]
	v_mfma_f32_16x16x32_bf16 v[104:107], v[204:207], v[164:167], v[104:107]
	v_mfma_f32_16x16x32_bf16 v[92:95], v[192:195], v[172:175], v[92:95]
	v_mfma_f32_16x16x32_bf16 v[88:91], v[204:207], v[172:175], v[88:91]
	v_mfma_f32_16x16x32_bf16 v[84:87], v[192:195], v[184:187], v[84:87]
	v_mfma_f32_16x16x32_bf16 v[80:83], v[204:207], v[184:187], v[80:83]
	v_mfma_f32_16x16x32_bf16 v[132:135], v[196:199], v[160:163], v[132:135]
	v_mfma_f32_16x16x32_bf16 v[128:131], v[212:215], v[160:163], v[128:131]
	v_mfma_f32_16x16x32_bf16 v[108:111], v[196:199], v[168:171], v[108:111]
	v_mfma_f32_16x16x32_bf16 v[104:107], v[212:215], v[168:171], v[104:107]
	v_mfma_f32_16x16x32_bf16 v[92:95], v[196:199], v[180:183], v[92:95]
	v_mfma_f32_16x16x32_bf16 v[88:91], v[212:215], v[180:183], v[88:91]
	v_mfma_f32_16x16x32_bf16 v[84:87], v[196:199], v[188:191], v[84:87]
	v_mfma_f32_16x16x32_bf16 v[80:83], v[212:215], v[188:191], v[80:83]
	s_add_i32 m0, s56, 0xffffff80
	s_barrier
	ds_read_b128 v[156:159], v155 offset:49152
	ds_read_b128 v[160:163], v155 offset:50176
	ds_read_b128 v[164:167], v155 offset:51200
	ds_read_b128 v[168:171], v155 offset:52224
	ds_read_b128 v[172:175], v155 offset:53248
	ds_read_b128 v[180:183], v155 offset:54272
	ds_read_b128 v[184:187], v155 offset:55296
	ds_read_b128 v[188:191], v155 offset:56320
	global_load_lds_dwordx4 v178, s[100:101] offset:128
	s_add_i32 m0, s57, 0xffffff80
	s_nop 0
	global_load_lds_dwordx4 v144, s[100:101] offset:128
	s_barrier
	s_waitcnt lgkmcnt(0)
	v_mfma_f32_16x16x32_bf16 v[64:67], v[56:59], v[156:159], v[64:67]
	v_mfma_f32_16x16x32_bf16 v[60:63], v[72:75], v[156:159], v[60:63]
	v_mfma_f32_16x16x32_bf16 v[44:47], v[56:59], v[164:167], v[44:47]
	v_mfma_f32_16x16x32_bf16 v[40:43], v[72:75], v[164:167], v[40:43]
	v_mfma_f32_16x16x32_bf16 v[28:31], v[56:59], v[172:175], v[28:31]
	v_mfma_f32_16x16x32_bf16 v[24:27], v[72:75], v[172:175], v[24:27]
	v_mfma_f32_16x16x32_bf16 v[12:15], v[56:59], v[184:187], v[12:15]
	v_mfma_f32_16x16x32_bf16 v[8:11], v[72:75], v[184:187], v[8:11]
	v_mfma_f32_16x16x32_bf16 v[64:67], v[68:71], v[160:163], v[64:67]
	v_mfma_f32_16x16x32_bf16 v[60:63], v[76:79], v[160:163], v[60:63]
	v_mfma_f32_16x16x32_bf16 v[44:47], v[68:71], v[168:171], v[44:47]
	v_mfma_f32_16x16x32_bf16 v[40:43], v[76:79], v[168:171], v[40:43]
	v_mfma_f32_16x16x32_bf16 v[28:31], v[68:71], v[180:183], v[28:31]
	v_mfma_f32_16x16x32_bf16 v[24:27], v[76:79], v[180:183], v[24:27]
	v_mfma_f32_16x16x32_bf16 v[12:15], v[68:71], v[188:191], v[12:15]
	v_mfma_f32_16x16x32_bf16 v[8:11], v[76:79], v[188:191], v[8:11]
	s_barrier
	s_add_u32 s14, s18, 0x158080
	s_addc_u32 s15, s19, 0
	s_add_i32 s18, s20, s28
	s_mov_b32 m0, s18
	s_nop 0
	global_load_lds_dwordx4 v178, s[14:15]
	s_add_i32 m0, s18, 0x2000
	s_nop 0
	global_load_lds_dwordx4 v144, s[14:15]
	s_waitcnt vmcnt(6)
	s_barrier
	v_mfma_f32_16x16x32_bf16 v[48:51], v[192:195], v[156:159], v[48:51]
	v_mfma_f32_16x16x32_bf16 v[56:59], v[196:199], v[160:163], v[48:51]
	v_mfma_f32_16x16x32_bf16 v[48:51], v[204:207], v[156:159], v[52:55]
	v_mfma_f32_16x16x32_bf16 v[36:39], v[192:195], v[164:167], v[36:39]
	v_mfma_f32_16x16x32_bf16 v[32:35], v[204:207], v[164:167], v[32:35]
	v_mfma_f32_16x16x32_bf16 v[20:23], v[192:195], v[172:175], v[20:23]
	v_mfma_f32_16x16x32_bf16 v[16:19], v[204:207], v[172:175], v[16:19]
	v_mfma_f32_16x16x32_bf16 v[4:7], v[192:195], v[184:187], v[4:7]
	v_mfma_f32_16x16x32_bf16 v[0:3], v[204:207], v[184:187], v[0:3]
	v_mfma_f32_16x16x32_bf16 v[52:55], v[212:215], v[160:163], v[48:51]
	v_mfma_f32_16x16x32_bf16 v[36:39], v[196:199], v[168:171], v[36:39]
	v_mfma_f32_16x16x32_bf16 v[32:35], v[212:215], v[168:171], v[32:35]
	v_mfma_f32_16x16x32_bf16 v[20:23], v[196:199], v[180:183], v[20:23]
	v_mfma_f32_16x16x32_bf16 v[16:19], v[212:215], v[180:183], v[16:19]
	v_mfma_f32_16x16x32_bf16 v[4:7], v[196:199], v[188:191], v[4:7]
	v_mfma_f32_16x16x32_bf16 v[0:3], v[212:215], v[188:191], v[0:3]
	s_add_i32 s67, s67, 2
	s_add_u32 s63, s63, 0x100
	s_addc_u32 s66, s66, 0
	s_cmpk_gt_u32 s67, 0x53
	s_mov_b64 s[14:15], s[16:17]
	s_barrier
	s_cbranch_scc0 .LBB0_1363
	s_lshl_b32 s12, s61, 8
	s_add_i32 s10, s12, 0xfffff000
	s_ashr_i32 s10, s10, 11
	s_add_i32 s10, s10, 1
	s_cmp_gt_i32 s61, 15
	s_cselect_b32 s10, s10, 0
	v_add_u32_e32 v162, s12, v152
	v_lshl_or_b32 v48, s62, 8, v154
	s_mul_hi_i32 s11, s10, 0xc000
	s_mul_i32 s10, s10, 0xc000
	v_ashrrev_i32_e32 v163, 31, v162
	v_readlane_b32 s68, v252, 37
	s_add_u32 s10, s35, s10
	v_ashrrev_i32_e32 v49, 31, v48
	v_lshlrev_b64 v[150:151], 13, v[162:163]
	v_readlane_b32 s82, v252, 51
	v_readlane_b32 s83, v252, 52
	s_addc_u32 s11, s39, s11
	v_lshlrev_b64 v[160:161], 2, v[48:49]
	v_lshl_add_u64 v[150:151], s[82:83], 0, v[150:151]
	v_lshl_add_u64 v[48:49], s[10:11], 0, v[160:161]
	v_lshl_add_u64 v[150:151], v[150:151], 0, v[160:161]
	global_load_dwordx4 v[76:79], v[48:49], off
	global_load_dwordx4 v[72:75], v[48:49], off offset:64
	global_load_dwordx4 v[68:71], v[48:49], off offset:512
	s_nop 0
	global_load_dwordx4 v[48:51], v[48:49], off offset:576
	s_mov_b64 s[10:11], 0x100000
	s_mov_b32 s62, s59
	s_mov_b32 s61, s60
	s_mov_b64 s[16:17], s[6:7]
	s_mov_b64 s[14:15], s[8:9]
	v_readlane_b32 s69, v252, 38
	v_readlane_b32 s70, v252, 39
	v_readlane_b32 s71, v252, 40
	v_readlane_b32 s72, v252, 41
	v_readlane_b32 s73, v252, 42
	v_readlane_b32 s74, v252, 43
	v_readlane_b32 s75, v252, 44
	v_readlane_b32 s76, v252, 45
	v_readlane_b32 s77, v252, 46
	v_readlane_b32 s78, v252, 47
	v_readlane_b32 s79, v252, 48
	v_readlane_b32 s80, v252, 49
	v_readlane_b32 s81, v252, 50
	s_and_b64 vcc, exec, s[4:5]
	s_nop 4
	v_lshl_add_u32 v145, v162, 13, v160
	v_add_u32_e32 v156, 0x20000, v145
	v_add_u32_e32 v158, 0x40000, v145
	v_add_u32_e32 v159, 0x60000, v145
	v_add_u32_e32 v176, 0x100000, v145
	v_add_u32_e32 v177, 0x120000, v145
	v_add_u32_e32 v223, 0x140000, v145
	v_add_u32_e32 v248, 0x160000, v145
	global_load_dwordx4 v[164:167], v145, s[82:83]
	global_load_dwordx4 v[168:171], v145, s[82:83] offset:64
	global_load_dwordx4 v[172:175], v145, s[82:83] offset:512
	global_load_dwordx4 v[180:183], v145, s[82:83] offset:576
	global_load_dwordx4 v[184:187], v156, s[82:83]
	global_load_dwordx4 v[188:191], v156, s[82:83] offset:64
	global_load_dwordx4 v[192:195], v156, s[82:83] offset:512
	global_load_dwordx4 v[196:199], v156, s[82:83] offset:576
	global_load_dwordx4 v[204:207], v158, s[82:83]
	global_load_dwordx4 v[212:215], v158, s[82:83] offset:64
	global_load_dwordx4 v[224:227], v158, s[82:83] offset:512
	global_load_dwordx4 v[228:231], v158, s[82:83] offset:576
	global_load_dwordx4 v[232:235], v159, s[82:83]
	global_load_dwordx4 v[236:239], v159, s[82:83] offset:64
	global_load_dwordx4 v[240:243], v159, s[82:83] offset:512
	global_load_dwordx4 v[244:247], v159, s[82:83] offset:576
	s_waitcnt vmcnt(15)
	v_pk_fma_f32 v[142:143], v[142:143], v[78:79], v[166:167]
	v_pk_fma_f32 v[140:141], v[140:141], v[76:77], v[164:165]
	global_store_dwordx4 v145, v[140:143], s[82:83]
	global_load_dwordx4 v[164:167], v176, s[82:83]
	s_waitcnt vmcnt(16)
	v_pk_fma_f32 v[138:139], v[138:139], v[74:75], v[170:171]
	v_pk_fma_f32 v[136:137], v[136:137], v[72:73], v[168:169]
	global_store_dwordx4 v145, v[136:139], s[82:83] offset:64
	global_load_dwordx4 v[168:171], v176, s[82:83] offset:64
	s_waitcnt vmcnt(17)
	v_pk_fma_f32 v[134:135], v[134:135], v[70:71], v[174:175]
	v_pk_fma_f32 v[132:133], v[132:133], v[68:69], v[172:173]
	global_store_dwordx4 v145, v[132:135], s[82:83] offset:512
	global_load_dwordx4 v[172:175], v176, s[82:83] offset:512
	s_waitcnt vmcnt(18)
	v_pk_fma_f32 v[130:131], v[130:131], v[50:51], v[182:183]
	v_pk_fma_f32 v[128:129], v[128:129], v[48:49], v[180:181]
	global_store_dwordx4 v145, v[128:131], s[82:83] offset:576
	global_load_dwordx4 v[180:183], v176, s[82:83] offset:576
	s_waitcnt vmcnt(19)
	v_pk_fma_f32 v[126:127], v[126:127], v[78:79], v[186:187]
	v_pk_fma_f32 v[124:125], v[124:125], v[76:77], v[184:185]
	global_store_dwordx4 v156, v[124:127], s[82:83]
	global_load_dwordx4 v[184:187], v177, s[82:83]
	s_waitcnt vmcnt(20)
	v_pk_fma_f32 v[122:123], v[122:123], v[74:75], v[190:191]
	v_pk_fma_f32 v[120:121], v[120:121], v[72:73], v[188:189]
	global_store_dwordx4 v156, v[120:123], s[82:83] offset:64
	global_load_dwordx4 v[188:191], v177, s[82:83] offset:64
	s_waitcnt vmcnt(21)
	v_pk_fma_f32 v[110:111], v[110:111], v[70:71], v[194:195]
	v_pk_fma_f32 v[108:109], v[108:109], v[68:69], v[192:193]
	global_store_dwordx4 v156, v[108:111], s[82:83] offset:512
	global_load_dwordx4 v[192:195], v177, s[82:83] offset:512
	s_waitcnt vmcnt(22)
	v_pk_fma_f32 v[106:107], v[106:107], v[50:51], v[198:199]
	v_pk_fma_f32 v[104:105], v[104:105], v[48:49], v[196:197]
	global_store_dwordx4 v156, v[104:107], s[82:83] offset:576
	global_load_dwordx4 v[196:199], v177, s[82:83] offset:576
	s_waitcnt vmcnt(23)
	v_pk_fma_f32 v[118:119], v[118:119], v[78:79], v[206:207]
	v_pk_fma_f32 v[116:117], v[116:117], v[76:77], v[204:205]
	global_store_dwordx4 v158, v[116:119], s[82:83]
	global_load_dwordx4 v[204:207], v223, s[82:83]
	s_waitcnt vmcnt(24)
	v_pk_fma_f32 v[114:115], v[114:115], v[74:75], v[214:215]
	v_pk_fma_f32 v[112:113], v[112:113], v[72:73], v[212:213]
	global_store_dwordx4 v158, v[112:115], s[82:83] offset:64
	global_load_dwordx4 v[212:215], v223, s[82:83] offset:64
	s_waitcnt vmcnt(25)
	v_pk_fma_f32 v[94:95], v[94:95], v[70:71], v[226:227]
	v_pk_fma_f32 v[92:93], v[92:93], v[68:69], v[224:225]
	global_store_dwordx4 v158, v[92:95], s[82:83] offset:512
	global_load_dwordx4 v[224:227], v223, s[82:83] offset:512
	s_waitcnt vmcnt(26)
	v_pk_fma_f32 v[90:91], v[90:91], v[50:51], v[230:231]
	v_pk_fma_f32 v[88:89], v[88:89], v[48:49], v[228:229]
	global_store_dwordx4 v158, v[88:91], s[82:83] offset:576
	global_load_dwordx4 v[228:231], v223, s[82:83] offset:576
	s_waitcnt vmcnt(27)
	v_pk_fma_f32 v[102:103], v[102:103], v[78:79], v[234:235]
	v_pk_fma_f32 v[100:101], v[100:101], v[76:77], v[232:233]
	global_store_dwordx4 v159, v[100:103], s[82:83]
	global_load_dwordx4 v[232:235], v248, s[82:83]
	s_waitcnt vmcnt(28)
	v_pk_fma_f32 v[98:99], v[98:99], v[74:75], v[238:239]
	v_pk_fma_f32 v[96:97], v[96:97], v[72:73], v[236:237]
	global_store_dwordx4 v159, v[96:99], s[82:83] offset:64
	global_load_dwordx4 v[236:239], v248, s[82:83] offset:64
	s_waitcnt vmcnt(29)
	v_pk_fma_f32 v[86:87], v[86:87], v[70:71], v[242:243]
	v_pk_fma_f32 v[84:85], v[84:85], v[68:69], v[240:241]
	global_store_dwordx4 v159, v[84:87], s[82:83] offset:512
	global_load_dwordx4 v[240:243], v248, s[82:83] offset:512
	s_waitcnt vmcnt(30)
	v_pk_fma_f32 v[82:83], v[82:83], v[50:51], v[246:247]
	v_pk_fma_f32 v[80:81], v[80:81], v[48:49], v[244:245]
	global_store_dwordx4 v159, v[80:83], s[82:83] offset:576
	global_load_dwordx4 v[244:247], v248, s[82:83] offset:576
	s_waitcnt vmcnt(30)
	v_pk_fma_f32 v[66:67], v[66:67], v[78:79], v[166:167]
	v_pk_fma_f32 v[64:65], v[64:65], v[76:77], v[164:165]
	global_store_dwordx4 v176, v[64:67], s[82:83]
	s_waitcnt vmcnt(29)
	v_pk_fma_f32 v[62:63], v[62:63], v[74:75], v[170:171]
	v_pk_fma_f32 v[60:61], v[60:61], v[72:73], v[168:169]
	global_store_dwordx4 v176, v[60:63], s[82:83] offset:64
	s_waitcnt vmcnt(28)
	v_pk_fma_f32 v[58:59], v[58:59], v[70:71], v[174:175]
	v_pk_fma_f32 v[56:57], v[56:57], v[68:69], v[172:173]
	global_store_dwordx4 v176, v[56:59], s[82:83] offset:512
	s_waitcnt vmcnt(27)
	v_pk_fma_f32 v[54:55], v[54:55], v[50:51], v[182:183]
	v_pk_fma_f32 v[52:53], v[52:53], v[48:49], v[180:181]
	global_store_dwordx4 v176, v[52:55], s[82:83] offset:576
	s_waitcnt vmcnt(26)
	v_pk_fma_f32 v[46:47], v[46:47], v[78:79], v[186:187]
	v_pk_fma_f32 v[44:45], v[44:45], v[76:77], v[184:185]
	global_store_dwordx4 v177, v[44:47], s[82:83]
	s_waitcnt vmcnt(25)
	v_pk_fma_f32 v[42:43], v[42:43], v[74:75], v[190:191]
	v_pk_fma_f32 v[40:41], v[40:41], v[72:73], v[188:189]
	global_store_dwordx4 v177, v[40:43], s[82:83] offset:64
	s_waitcnt vmcnt(24)
	v_pk_fma_f32 v[38:39], v[38:39], v[70:71], v[194:195]
	v_pk_fma_f32 v[36:37], v[36:37], v[68:69], v[192:193]
	global_store_dwordx4 v177, v[36:39], s[82:83] offset:512
	s_waitcnt vmcnt(23)
	v_pk_fma_f32 v[34:35], v[34:35], v[50:51], v[198:199]
	v_pk_fma_f32 v[32:33], v[32:33], v[48:49], v[196:197]
	global_store_dwordx4 v177, v[32:35], s[82:83] offset:576
	s_waitcnt vmcnt(22)
	v_pk_fma_f32 v[30:31], v[30:31], v[78:79], v[206:207]
	v_pk_fma_f32 v[28:29], v[28:29], v[76:77], v[204:205]
	global_store_dwordx4 v223, v[28:31], s[82:83]
	s_waitcnt vmcnt(21)
	v_pk_fma_f32 v[26:27], v[26:27], v[74:75], v[214:215]
	v_pk_fma_f32 v[24:25], v[24:25], v[72:73], v[212:213]
	global_store_dwordx4 v223, v[24:27], s[82:83] offset:64
	s_waitcnt vmcnt(20)
	v_pk_fma_f32 v[22:23], v[22:23], v[70:71], v[226:227]
	v_pk_fma_f32 v[20:21], v[20:21], v[68:69], v[224:225]
	global_store_dwordx4 v223, v[20:23], s[82:83] offset:512
	s_waitcnt vmcnt(19)
	v_pk_fma_f32 v[18:19], v[18:19], v[50:51], v[230:231]
	v_pk_fma_f32 v[16:17], v[16:17], v[48:49], v[228:229]
	global_store_dwordx4 v223, v[16:19], s[82:83] offset:576
	s_waitcnt vmcnt(18)
	v_pk_fma_f32 v[14:15], v[14:15], v[78:79], v[234:235]
	v_pk_fma_f32 v[12:13], v[12:13], v[76:77], v[232:233]
	global_store_dwordx4 v248, v[12:15], s[82:83]
	s_waitcnt vmcnt(17)
	v_pk_fma_f32 v[10:11], v[10:11], v[74:75], v[238:239]
	v_pk_fma_f32 v[8:9], v[8:9], v[72:73], v[236:237]
	global_store_dwordx4 v248, v[8:11], s[82:83] offset:64
	s_waitcnt vmcnt(16)
	v_pk_fma_f32 v[6:7], v[6:7], v[70:71], v[242:243]
	v_pk_fma_f32 v[4:5], v[4:5], v[68:69], v[240:241]
	global_store_dwordx4 v248, v[4:7], s[82:83] offset:512
	s_waitcnt vmcnt(15)
	v_pk_fma_f32 v[2:3], v[2:3], v[50:51], v[246:247]
	v_pk_fma_f32 v[0:1], v[0:1], v[48:49], v[244:245]
	global_store_dwordx4 v248, v[0:3], s[82:83] offset:576
	s_mov_b64 s[10:11], 0x160000
	s_cbranch_vccz .LBB0_1360
	s_waitcnt vmcnt(0)
	s_mov_b32 s4, s86
	s_cmp_gt_u32 s4, 3
	s_movk_i32 s57, 0x404
	s_cbranch_scc1 .LBB0_1367
	s_barrier
